# sample SSM items moved from the pass A phase to the start of the pass C phase on waves 0-3 (latency-bound work beside the partner wave's VALU-bound pass C)
# speedup vs baseline: 1.0631x; 1.0055x over previous
.LBB0_1308:
	s_or_b64 exec, exec, s[2:3]
	v_readlane_b32 s0, v255, 3
	v_readlane_b32 s1, v255, 4
	s_waitcnt lgkmcnt(0)
	s_barrier
	s_mov_b32 s98, 0
	s_load_dwordx4 s[52:55], s[0:1], 0xc8
	s_load_dwordx2 s[2:3], s[0:1], 0xa0
	s_load_dwordx4 s[56:59], s[0:1], 0x28
	s_load_dwordx4 s[60:63], s[0:1], 0x90
	v_readlane_b32 s0, v255, 18
	s_waitcnt lgkmcnt(0)
	s_add_u32 s64, s54, 0x5200000
	s_addc_u32 s65, s55, 0
	v_mov_b32_e32 v2, v0
	s_add_u32 s66, s54, 0x30000
	v_readlane_b32 s1, v255, 19
	s_addc_u32 s67, s55, 0
	s_andn2_b64 vcc, exec, s[0:1]
	v_readfirstlane_b32 s0, v2
	s_cbranch_vccnz .LBB0_1315
	s_cmp_eq_u32 s97, 0x100
	s_cbranch_scc0 .Lpa_compiled
	v_readlane_b32 s6, v255, 7
	v_readlane_b32 s7, v255, 2
	s_nop 0
	s_lshr_b32 s7, s7, 6
	s_and_b32 s8, s6, 15
	s_lshl_b32 s8, s8, 3
	s_add_i32 s8, s8, s7
	s_bfe_u32 s9, s6, 0x30004
	s_lshr_b32 s10, s6, 7
	s_lshl_b32 s11, s8, 9
	s_add_u32 s34, s54, 0x30000
	s_addc_u32 s35, s55, 0
	s_add_u32 s34, s34, s11
	s_addc_u32 s35, s35, 0
	s_lshl_b32 s11, s8, 12
	s_add_u32 s36, s54, 0x140000
	s_addc_u32 s37, s55, 0
	s_add_u32 s36, s36, s11
	s_addc_u32 s37, s37, 0
	s_lshl_b32 s11, s10, 24
	s_lshl_b32 s14, s9, 21
	s_add_i32 s11, s11, s14
	s_lshl_b32 s14, s8, 5
	s_add_i32 s11, s11, s14
	s_add_u32 s32, s54, 0x5200000
	s_addc_u32 s33, s55, 0
	s_add_u32 s32, s32, s11
	s_addc_u32 s33, s33, 0
	s_lshl_b32 s11, s10, 7
	s_add_i32 s11, s11, s8
	s_lshl_b32 s11, s11, 5
	s_lshl_b32 s14, s9, 2
	s_add_i32 s11, s11, s14
	s_lshl_b32 s11, s11, 9
	s_add_u32 s38, s54, 0x600000
	s_addc_u32 s39, s55, 0
	s_add_u32 s38, s38, s11
	s_addc_u32 s39, s39, 0
	s_mov_b32 s12, -1
	s_mov_b32 s13, 0
	v_and_b32_e32 v219, 63, v0
	v_and_b32_e32 v220, 31, v219
	v_lshrrev_b32_e32 v221, 5, v219
	v_xor_b32_e32 v208, 32, v219
	v_lshlrev_b32_e32 v208, 2, v208
	v_lshlrev_b32_e32 v209, 2, v220
	v_lshlrev_b32_e32 v210, 12, v220
	v_lshl_add_u32 v210, v221, 4, v210
	v_lshlrev_b32_e32 v222, 3, v220
	v_lshlrev_b32_e32 v223, 4, v219
	v_cmp_lt_u32_e64 s[40:41], 31, v219
	global_load_dwordx2 v[228:229], v222, s[34:35]
	global_load_dwordx2 v[244:245], v222, s[34:35] offset:256
	global_load_dwordx4 v[6:9], v223, s[36:37] offset:0
	global_load_dwordx4 v[10:13], v223, s[36:37] offset:1024
	global_load_dwordx4 v[14:17], v223, s[36:37] offset:2048
	global_load_dwordx4 v[18:21], v223, s[36:37] offset:3072
	s_add_u32 s42, s32, 0x0
	s_addc_u32 s43, s33, 0
	global_load_dwordx4 v[192:195], v210, s[42:43]
	s_add_u32 s42, s32, 0x20000
	s_addc_u32 s43, s33, 0
	global_load_dwordx4 v[196:199], v210, s[42:43]
	s_add_u32 s42, s32, 0x40000
	s_addc_u32 s43, s33, 0
	global_load_dwordx4 v[200:203], v210, s[42:43]
	s_add_u32 s42, s32, 0x60000
	s_addc_u32 s43, s33, 0
	global_load_dwordx4 v[204:207], v210, s[42:43]
	s_waitcnt vmcnt(9)
	v_mul_f32_e32 v242, v229, v229
	v_fma_f32 v230, v228, v228, -v242
	v_mul_f32_e32 v242, v229, v228
	v_fma_f32 v231, v228, v229, v242
	v_mul_f32_e32 v242, v231, v229
	v_fma_f32 v232, v230, v228, -v242
	v_mul_f32_e32 v242, v231, v228
	v_fma_f32 v233, v230, v229, v242
	v_mul_f32_e32 v242, v231, v231
	v_fma_f32 v234, v230, v230, -v242
	v_mul_f32_e32 v242, v231, v230
	v_fma_f32 v235, v230, v231, v242
	v_mul_f32_e32 v242, v235, v235
	v_fma_f32 v236, v234, v234, -v242
	v_mul_f32_e32 v242, v235, v234
	v_fma_f32 v237, v234, v235, v242
	v_mul_f32_e32 v242, v237, v237
	v_fma_f32 v238, v236, v236, -v242
	v_mul_f32_e32 v242, v237, v236
	v_fma_f32 v239, v236, v237, v242
	v_mul_f32_e32 v242, v239, v239
	v_fma_f32 v167, v238, v238, -v242
	v_mul_f32_e32 v242, v239, v238
	v_fma_f32 v168, v238, v239, v242
	v_cndmask_b32_e64 v240, v234, 1.0, s[40:41]
	v_cndmask_b32_e64 v241, v235, 0, s[40:41]
	v_mov_b32_e32 v101, v240
	v_mov_b32_e32 v117, v241
	v_mul_f32_e32 v242, v241, v229
	v_fma_f32 v100, v240, v228, -v242
	v_mul_f32_e32 v242, v241, v228
	v_fma_f32 v116, v240, v229, v242
	v_mul_f32_e32 v242, v241, v231
	v_fma_f32 v99, v240, v230, -v242
	v_mul_f32_e32 v242, v241, v230
	v_fma_f32 v115, v240, v231, v242
	v_mul_f32_e32 v242, v241, v233
	v_fma_f32 v98, v240, v232, -v242
	v_mul_f32_e32 v242, v241, v232
	v_fma_f32 v114, v240, v233, v242
	v_mul_f32_e32 v242, v117, v237
	v_fma_f32 v97, v101, v236, -v242
	v_mul_f32_e32 v242, v117, v236
	v_fma_f32 v113, v101, v237, v242
	v_mul_f32_e32 v242, v116, v237
	v_fma_f32 v96, v100, v236, -v242
	v_mul_f32_e32 v242, v116, v236
	v_fma_f32 v112, v100, v237, v242
	v_mul_f32_e32 v242, v115, v237
	v_fma_f32 v95, v99, v236, -v242
	v_mul_f32_e32 v242, v115, v236
	v_fma_f32 v111, v99, v237, v242
	v_mul_f32_e32 v242, v114, v237
	v_fma_f32 v94, v98, v236, -v242
	v_mul_f32_e32 v242, v114, v236
	v_fma_f32 v110, v98, v237, v242
	v_mul_f32_e32 v242, v113, v237
	v_fma_f32 v93, v97, v236, -v242
	v_mul_f32_e32 v242, v113, v236
	v_fma_f32 v109, v97, v237, v242
	v_mul_f32_e32 v242, v112, v237
	v_fma_f32 v92, v96, v236, -v242
	v_mul_f32_e32 v242, v112, v236
	v_fma_f32 v108, v96, v237, v242
	v_mul_f32_e32 v242, v111, v237
	v_fma_f32 v91, v95, v236, -v242
	v_mul_f32_e32 v242, v111, v236
	v_fma_f32 v107, v95, v237, v242
	v_mul_f32_e32 v242, v110, v237
	v_fma_f32 v90, v94, v236, -v242
	v_mul_f32_e32 v242, v110, v236
	v_fma_f32 v106, v94, v237, v242
	v_mul_f32_e32 v242, v109, v237
	v_fma_f32 v89, v93, v236, -v242
	v_mul_f32_e32 v242, v109, v236
	v_fma_f32 v105, v93, v237, v242
	v_mul_f32_e32 v242, v108, v237
	v_fma_f32 v88, v92, v236, -v242
	v_mul_f32_e32 v242, v108, v236
	v_fma_f32 v104, v92, v237, v242
	v_mul_f32_e32 v242, v107, v237
	v_fma_f32 v87, v91, v236, -v242
	v_mul_f32_e32 v242, v107, v236
	v_fma_f32 v103, v91, v237, v242
	v_mul_f32_e32 v242, v106, v237
	v_fma_f32 v86, v90, v236, -v242
	v_mul_f32_e32 v242, v106, v236
	v_fma_f32 v102, v90, v237, v242
	s_waitcnt vmcnt(8)
	v_mul_f32_e32 v242, v245, v245
	v_fma_f32 v230, v244, v244, -v242
	v_mul_f32_e32 v242, v245, v244
	v_fma_f32 v231, v244, v245, v242
	v_mul_f32_e32 v242, v231, v245
	v_fma_f32 v232, v230, v244, -v242
	v_mul_f32_e32 v242, v231, v244
	v_fma_f32 v233, v230, v245, v242
	v_mul_f32_e32 v242, v231, v231
	v_fma_f32 v234, v230, v230, -v242
	v_mul_f32_e32 v242, v231, v230
	v_fma_f32 v235, v230, v231, v242
	v_mul_f32_e32 v242, v235, v235
	v_fma_f32 v236, v234, v234, -v242
	v_mul_f32_e32 v242, v235, v234
	v_fma_f32 v237, v234, v235, v242
	v_mul_f32_e32 v242, v237, v237
	v_fma_f32 v238, v236, v236, -v242
	v_mul_f32_e32 v242, v237, v236
	v_fma_f32 v239, v236, v237, v242
	v_mul_f32_e32 v242, v239, v239
	v_fma_f32 v169, v238, v238, -v242
	v_mul_f32_e32 v242, v239, v238
	v_fma_f32 v170, v238, v239, v242
	v_cndmask_b32_e64 v240, v234, 1.0, s[40:41]
	v_cndmask_b32_e64 v241, v235, 0, s[40:41]
	v_mov_b32_e32 v133, v240
	v_mov_b32_e32 v149, v241
	v_mul_f32_e32 v242, v241, v245
	v_fma_f32 v132, v240, v244, -v242
	v_mul_f32_e32 v242, v241, v244
	v_fma_f32 v148, v240, v245, v242
	v_mul_f32_e32 v242, v241, v231
	v_fma_f32 v131, v240, v230, -v242
	v_mul_f32_e32 v242, v241, v230
	v_fma_f32 v147, v240, v231, v242
	v_mul_f32_e32 v242, v241, v233
	v_fma_f32 v130, v240, v232, -v242
	v_mul_f32_e32 v242, v241, v232
	v_fma_f32 v146, v240, v233, v242
	v_mul_f32_e32 v242, v149, v237
	v_fma_f32 v129, v133, v236, -v242
	v_mul_f32_e32 v242, v149, v236
	v_fma_f32 v145, v133, v237, v242
	v_mul_f32_e32 v242, v148, v237
	v_fma_f32 v128, v132, v236, -v242
	v_mul_f32_e32 v242, v148, v236
	v_fma_f32 v144, v132, v237, v242
	v_mul_f32_e32 v242, v147, v237
	v_fma_f32 v127, v131, v236, -v242
	v_mul_f32_e32 v242, v147, v236
	v_fma_f32 v143, v131, v237, v242
	v_mul_f32_e32 v242, v146, v237
	v_fma_f32 v126, v130, v236, -v242
	v_mul_f32_e32 v242, v146, v236
	v_fma_f32 v142, v130, v237, v242
	v_mul_f32_e32 v242, v145, v237
	v_fma_f32 v125, v129, v236, -v242
	v_mul_f32_e32 v242, v145, v236
	v_fma_f32 v141, v129, v237, v242
	v_mul_f32_e32 v242, v144, v237
	v_fma_f32 v124, v128, v236, -v242
	v_mul_f32_e32 v242, v144, v236
	v_fma_f32 v140, v128, v237, v242
	v_mul_f32_e32 v242, v143, v237
	v_fma_f32 v123, v127, v236, -v242
	v_mul_f32_e32 v242, v143, v236
	v_fma_f32 v139, v127, v237, v242
	v_mul_f32_e32 v242, v142, v237
	v_fma_f32 v122, v126, v236, -v242
	v_mul_f32_e32 v242, v142, v236
	v_fma_f32 v138, v126, v237, v242
	v_mul_f32_e32 v242, v141, v237
	v_fma_f32 v121, v125, v236, -v242
	v_mul_f32_e32 v242, v141, v236
	v_fma_f32 v137, v125, v237, v242
	v_mul_f32_e32 v242, v140, v237
	v_fma_f32 v120, v124, v236, -v242
	v_mul_f32_e32 v242, v140, v236
	v_fma_f32 v136, v124, v237, v242
	v_mul_f32_e32 v242, v139, v237
	v_fma_f32 v119, v123, v236, -v242
	v_mul_f32_e32 v242, v139, v236
	v_fma_f32 v135, v123, v237, v242
	v_mul_f32_e32 v242, v138, v237
	v_fma_f32 v118, v122, v236, -v242
	v_mul_f32_e32 v242, v138, v236
	v_fma_f32 v134, v122, v237, v242
	v_mov_b32_e32 v171, 0
	v_mov_b32_e32 v172, 0
	v_mov_b32_e32 v173, 0
	v_mov_b32_e32 v174, 0
	s_waitcnt vmcnt(3)
	v_mfma_f32_32x32x16_bf16 v[22:37], v[192:195], v[6:9], 0
	v_mfma_f32_32x32x16_bf16 v[54:69], v[192:195], v[14:17], 0
	v_mfma_f32_32x32x16_bf16 v[38:53], v[192:195], v[10:13], 0
	v_mfma_f32_32x32x16_bf16 v[70:85], v[192:195], v[18:21], 0
	s_add_u32 s42, s32, 0x80000
	s_addc_u32 s43, s33, 0
	global_load_dwordx4 v[192:195], v210, s[42:43]
	s_nop 7
	s_nop 3
	v_mul_f32_e32 v175, v86, v22
	v_mul_f32_e32 v179, v86, v54
	v_fma_f32 v175, -v102, v54, v175
	v_fmac_f32_e32 v179, v102, v22
	v_mul_f32_e32 v176, v87, v23
	v_mul_f32_e32 v180, v87, v55
	v_fma_f32 v176, -v103, v55, v176
	v_fmac_f32_e32 v180, v103, v23
	v_mul_f32_e32 v177, v88, v24
	v_mul_f32_e32 v181, v88, v56
	v_fma_f32 v177, -v104, v56, v177
	v_fmac_f32_e32 v181, v104, v24
	v_mul_f32_e32 v178, v89, v25
	v_mul_f32_e32 v182, v89, v57
	v_fma_f32 v178, -v105, v57, v178
	v_fmac_f32_e32 v182, v105, v25
	v_fmac_f32_e32 v175, v90, v26
	v_fmac_f32_e32 v179, v90, v58
	v_fma_f32 v175, -v106, v58, v175
	v_fmac_f32_e32 v179, v106, v26
	v_fmac_f32_e32 v176, v91, v27
	v_fmac_f32_e32 v180, v91, v59
	v_fma_f32 v176, -v107, v59, v176
	v_fmac_f32_e32 v180, v107, v27
	v_fmac_f32_e32 v177, v92, v28
	v_fmac_f32_e32 v181, v92, v60
	v_fma_f32 v177, -v108, v60, v177
	v_fmac_f32_e32 v181, v108, v28
	v_fmac_f32_e32 v178, v93, v29
	v_fmac_f32_e32 v182, v93, v61
	v_fma_f32 v178, -v109, v61, v178
	v_fmac_f32_e32 v182, v109, v29
	v_fmac_f32_e32 v175, v94, v30
	v_fmac_f32_e32 v179, v94, v62
	v_fma_f32 v175, -v110, v62, v175
	v_fmac_f32_e32 v179, v110, v30
	v_fmac_f32_e32 v176, v95, v31
	v_fmac_f32_e32 v180, v95, v63
	v_fma_f32 v176, -v111, v63, v176
	v_fmac_f32_e32 v180, v111, v31
	v_fmac_f32_e32 v177, v96, v32
	v_fmac_f32_e32 v181, v96, v64
	v_fma_f32 v177, -v112, v64, v177
	v_fmac_f32_e32 v181, v112, v32
	v_fmac_f32_e32 v178, v97, v33
	v_fmac_f32_e32 v182, v97, v65
	v_fma_f32 v178, -v113, v65, v178
	v_fmac_f32_e32 v182, v113, v33
	v_fmac_f32_e32 v175, v98, v34
	v_fmac_f32_e32 v179, v98, v66
	v_fma_f32 v175, -v114, v66, v175
	v_fmac_f32_e32 v179, v114, v34
	v_fmac_f32_e32 v176, v99, v35
	v_fmac_f32_e32 v180, v99, v67
	v_fma_f32 v176, -v115, v67, v176
	v_fmac_f32_e32 v180, v115, v35
	v_fmac_f32_e32 v177, v100, v36
	v_fmac_f32_e32 v181, v100, v68
	v_fma_f32 v177, -v116, v68, v177
	v_fmac_f32_e32 v181, v116, v36
	v_fmac_f32_e32 v178, v101, v37
	v_fmac_f32_e32 v182, v101, v69
	v_fma_f32 v178, -v117, v69, v178
	v_fmac_f32_e32 v182, v117, v37
	v_mul_f32_e32 v183, v118, v38
	v_mul_f32_e32 v187, v118, v70
	v_fma_f32 v183, -v134, v70, v183
	v_fmac_f32_e32 v187, v134, v38
	v_mul_f32_e32 v184, v119, v39
	v_mul_f32_e32 v188, v119, v71
	v_fma_f32 v184, -v135, v71, v184
	v_fmac_f32_e32 v188, v135, v39
	v_mul_f32_e32 v185, v120, v40
	v_mul_f32_e32 v189, v120, v72
	v_fma_f32 v185, -v136, v72, v185
	v_fmac_f32_e32 v189, v136, v40
	v_mul_f32_e32 v186, v121, v41
	v_mul_f32_e32 v190, v121, v73
	v_fma_f32 v186, -v137, v73, v186
	v_fmac_f32_e32 v190, v137, v41
	v_fmac_f32_e32 v183, v122, v42
	v_fmac_f32_e32 v187, v122, v74
	v_fma_f32 v183, -v138, v74, v183
	v_fmac_f32_e32 v187, v138, v42
	v_fmac_f32_e32 v184, v123, v43
	v_fmac_f32_e32 v188, v123, v75
	v_fma_f32 v184, -v139, v75, v184
	v_fmac_f32_e32 v188, v139, v43
	v_fmac_f32_e32 v185, v124, v44
	v_fmac_f32_e32 v189, v124, v76
	v_fma_f32 v185, -v140, v76, v185
	v_fmac_f32_e32 v189, v140, v44
	v_fmac_f32_e32 v186, v125, v45
	v_fmac_f32_e32 v190, v125, v77
	v_fma_f32 v186, -v141, v77, v186
	v_fmac_f32_e32 v190, v141, v45
	v_fmac_f32_e32 v183, v126, v46
	v_fmac_f32_e32 v187, v126, v78
	v_fma_f32 v183, -v142, v78, v183
	v_fmac_f32_e32 v187, v142, v46
	v_fmac_f32_e32 v184, v127, v47
	v_fmac_f32_e32 v188, v127, v79
	v_fma_f32 v184, -v143, v79, v184
	v_fmac_f32_e32 v188, v143, v47
	v_fmac_f32_e32 v185, v128, v48
	v_fmac_f32_e32 v189, v128, v80
	v_fma_f32 v185, -v144, v80, v185
	v_fmac_f32_e32 v189, v144, v48
	v_fmac_f32_e32 v186, v129, v49
	v_fmac_f32_e32 v190, v129, v81
	v_fma_f32 v186, -v145, v81, v186
	v_fmac_f32_e32 v190, v145, v49
	v_fmac_f32_e32 v183, v130, v50
	v_fmac_f32_e32 v187, v130, v82
	v_fma_f32 v183, -v146, v82, v183
	v_fmac_f32_e32 v187, v146, v50
	v_fmac_f32_e32 v184, v131, v51
	v_fmac_f32_e32 v188, v131, v83
	v_fma_f32 v184, -v147, v83, v184
	v_fmac_f32_e32 v188, v147, v51
	v_fmac_f32_e32 v185, v132, v52
	v_fmac_f32_e32 v189, v132, v84
	v_fma_f32 v185, -v148, v84, v185
	v_fmac_f32_e32 v189, v148, v52
	v_fmac_f32_e32 v186, v133, v53
	v_fmac_f32_e32 v190, v133, v85
	v_fma_f32 v186, -v149, v85, v186
	v_fmac_f32_e32 v190, v149, v53
	s_waitcnt vmcnt(3)
	v_mfma_f32_32x32x16_bf16 v[22:37], v[196:199], v[6:9], 0
	v_mfma_f32_32x32x16_bf16 v[54:69], v[196:199], v[14:17], 0
	v_mfma_f32_32x32x16_bf16 v[38:53], v[196:199], v[10:13], 0
	v_mfma_f32_32x32x16_bf16 v[70:85], v[196:199], v[18:21], 0
	s_add_u32 s42, s32, 0xa0000
	s_addc_u32 s43, s33, 0
	global_load_dwordx4 v[196:199], v210, s[42:43]
	v_add_f32_e32 v219, v175, v176
	v_add_f32_e32 v220, v177, v178
	v_add_f32_e32 v211, v219, v220
	v_add_f32_e32 v219, v179, v180
	v_add_f32_e32 v220, v181, v182
	v_add_f32_e32 v212, v219, v220
	v_add_f32_e32 v219, v183, v184
	v_add_f32_e32 v220, v185, v186
	v_add_f32_e32 v213, v219, v220
	v_add_f32_e32 v219, v187, v188
	v_add_f32_e32 v220, v189, v190
	v_add_f32_e32 v214, v219, v220
	ds_bpermute_b32 v215, v208, v211
	ds_bpermute_b32 v216, v208, v212
	ds_bpermute_b32 v217, v208, v213
	ds_bpermute_b32 v218, v208, v214
	v_mul_f32_e32 v175, v86, v22
	v_mul_f32_e32 v179, v86, v54
	v_fma_f32 v175, -v102, v54, v175
	v_fmac_f32_e32 v179, v102, v22
	v_mul_f32_e32 v176, v87, v23
	v_mul_f32_e32 v180, v87, v55
	v_fma_f32 v176, -v103, v55, v176
	v_fmac_f32_e32 v180, v103, v23
	v_mul_f32_e32 v177, v88, v24
	v_mul_f32_e32 v181, v88, v56
	v_fma_f32 v177, -v104, v56, v177
	v_fmac_f32_e32 v181, v104, v24
	v_mul_f32_e32 v178, v89, v25
	v_mul_f32_e32 v182, v89, v57
	v_fma_f32 v178, -v105, v57, v178
	v_fmac_f32_e32 v182, v105, v25
	v_fmac_f32_e32 v175, v90, v26
	v_fmac_f32_e32 v179, v90, v58
	v_fma_f32 v175, -v106, v58, v175
	v_fmac_f32_e32 v179, v106, v26
	v_fmac_f32_e32 v176, v91, v27
	v_fmac_f32_e32 v180, v91, v59
	v_fma_f32 v176, -v107, v59, v176
	v_fmac_f32_e32 v180, v107, v27
	v_fmac_f32_e32 v177, v92, v28
	v_fmac_f32_e32 v181, v92, v60
	v_fma_f32 v177, -v108, v60, v177
	v_fmac_f32_e32 v181, v108, v28
	v_fmac_f32_e32 v178, v93, v29
	v_fmac_f32_e32 v182, v93, v61
	v_fma_f32 v178, -v109, v61, v178
	v_fmac_f32_e32 v182, v109, v29
	v_fmac_f32_e32 v175, v94, v30
	v_fmac_f32_e32 v179, v94, v62
	v_fma_f32 v175, -v110, v62, v175
	v_fmac_f32_e32 v179, v110, v30
	v_fmac_f32_e32 v176, v95, v31
	v_fmac_f32_e32 v180, v95, v63
	v_fma_f32 v176, -v111, v63, v176
	v_fmac_f32_e32 v180, v111, v31
	v_fmac_f32_e32 v177, v96, v32
	v_fmac_f32_e32 v181, v96, v64
	v_fma_f32 v177, -v112, v64, v177
	v_fmac_f32_e32 v181, v112, v32
	v_fmac_f32_e32 v178, v97, v33
	v_fmac_f32_e32 v182, v97, v65
	v_fma_f32 v178, -v113, v65, v178
	v_fmac_f32_e32 v182, v113, v33
	v_fmac_f32_e32 v175, v98, v34
	v_fmac_f32_e32 v179, v98, v66
	v_fma_f32 v175, -v114, v66, v175
	v_fmac_f32_e32 v179, v114, v34
	v_fmac_f32_e32 v176, v99, v35
	v_fmac_f32_e32 v180, v99, v67
	v_fma_f32 v176, -v115, v67, v176
	v_fmac_f32_e32 v180, v115, v35
	v_fmac_f32_e32 v177, v100, v36
	v_fmac_f32_e32 v181, v100, v68
	v_fma_f32 v177, -v116, v68, v177
	v_fmac_f32_e32 v181, v116, v36
	v_fmac_f32_e32 v178, v101, v37
	v_fmac_f32_e32 v182, v101, v69
	v_fma_f32 v178, -v117, v69, v178
	v_fmac_f32_e32 v182, v117, v37
	s_waitcnt lgkmcnt(0)
	v_add_f32_e32 v211, v211, v215
	v_add_f32_e32 v212, v212, v216
	v_add_f32_e32 v213, v213, v217
	v_add_f32_e32 v214, v214, v218
	v_fma_f32 v219, -v168, v172, v211
	v_fma_f32 v220, v168, v171, v212
	v_fma_f32 v171, v167, v171, v219
	v_fma_f32 v172, v167, v172, v220
	v_fma_f32 v219, -v170, v174, v213
	v_fma_f32 v220, v170, v173, v214
	v_fma_f32 v173, v169, v173, v219
	v_fma_f32 v174, v169, v174, v220
	v_mul_f32_e32 v183, v118, v38
	v_mul_f32_e32 v187, v118, v70
	v_fma_f32 v183, -v134, v70, v183
	v_fmac_f32_e32 v187, v134, v38
	v_mul_f32_e32 v184, v119, v39
	v_mul_f32_e32 v188, v119, v71
	v_fma_f32 v184, -v135, v71, v184
	v_fmac_f32_e32 v188, v135, v39
	v_mul_f32_e32 v185, v120, v40
	v_mul_f32_e32 v189, v120, v72
	v_fma_f32 v185, -v136, v72, v185
	v_fmac_f32_e32 v189, v136, v40
	v_mul_f32_e32 v186, v121, v41
	v_mul_f32_e32 v190, v121, v73
	v_fma_f32 v186, -v137, v73, v186
	v_fmac_f32_e32 v190, v137, v41
	v_fmac_f32_e32 v183, v122, v42
	v_fmac_f32_e32 v187, v122, v74
	v_fma_f32 v183, -v138, v74, v183
	v_fmac_f32_e32 v187, v138, v42
	v_fmac_f32_e32 v184, v123, v43
	v_fmac_f32_e32 v188, v123, v75
	v_fma_f32 v184, -v139, v75, v184
	v_fmac_f32_e32 v188, v139, v43
	v_fmac_f32_e32 v185, v124, v44
	v_fmac_f32_e32 v189, v124, v76
	v_fma_f32 v185, -v140, v76, v185
	v_fmac_f32_e32 v189, v140, v44
	v_fmac_f32_e32 v186, v125, v45
	v_fmac_f32_e32 v190, v125, v77
	v_fma_f32 v186, -v141, v77, v186
	v_fmac_f32_e32 v190, v141, v45
	v_fmac_f32_e32 v183, v126, v46
	v_fmac_f32_e32 v187, v126, v78
	v_fma_f32 v183, -v142, v78, v183
	v_fmac_f32_e32 v187, v142, v46
	v_fmac_f32_e32 v184, v127, v47
	v_fmac_f32_e32 v188, v127, v79
	v_fma_f32 v184, -v143, v79, v184
	v_fmac_f32_e32 v188, v143, v47
	v_fmac_f32_e32 v185, v128, v48
	v_fmac_f32_e32 v189, v128, v80
	v_fma_f32 v185, -v144, v80, v185
	v_fmac_f32_e32 v189, v144, v48
	v_fmac_f32_e32 v186, v129, v49
	v_fmac_f32_e32 v190, v129, v81
	v_fma_f32 v186, -v145, v81, v186
	v_fmac_f32_e32 v190, v145, v49
	v_fmac_f32_e32 v183, v130, v50
	v_fmac_f32_e32 v187, v130, v82
	v_fma_f32 v183, -v146, v82, v183
	v_fmac_f32_e32 v187, v146, v50
	v_fmac_f32_e32 v184, v131, v51
	v_fmac_f32_e32 v188, v131, v83
	v_fma_f32 v184, -v147, v83, v184
	v_fmac_f32_e32 v188, v147, v51
	v_fmac_f32_e32 v185, v132, v52
	v_fmac_f32_e32 v189, v132, v84
	v_fma_f32 v185, -v148, v84, v185
	v_fmac_f32_e32 v189, v148, v52
	v_fmac_f32_e32 v186, v133, v53
	v_fmac_f32_e32 v190, v133, v85
	v_fma_f32 v186, -v149, v85, v186
	v_fmac_f32_e32 v190, v149, v53
	s_waitcnt vmcnt(3)
	v_mfma_f32_32x32x16_bf16 v[22:37], v[200:203], v[6:9], 0
	v_mfma_f32_32x32x16_bf16 v[54:69], v[200:203], v[14:17], 0
	v_mfma_f32_32x32x16_bf16 v[38:53], v[200:203], v[10:13], 0
	v_mfma_f32_32x32x16_bf16 v[70:85], v[200:203], v[18:21], 0
	s_add_u32 s42, s32, 0xc0000
	s_addc_u32 s43, s33, 0
	global_load_dwordx4 v[200:203], v210, s[42:43]
	v_add_f32_e32 v219, v175, v176
	v_add_f32_e32 v220, v177, v178
	v_add_f32_e32 v211, v219, v220
	v_add_f32_e32 v219, v179, v180
	v_add_f32_e32 v220, v181, v182
	v_add_f32_e32 v212, v219, v220
	v_add_f32_e32 v219, v183, v184
	v_add_f32_e32 v220, v185, v186
	v_add_f32_e32 v213, v219, v220
	v_add_f32_e32 v219, v187, v188
	v_add_f32_e32 v220, v189, v190
	v_add_f32_e32 v214, v219, v220
	ds_bpermute_b32 v215, v208, v211
	ds_bpermute_b32 v216, v208, v212
	ds_bpermute_b32 v217, v208, v213
	ds_bpermute_b32 v218, v208, v214
	v_mul_f32_e32 v175, v86, v22
	v_mul_f32_e32 v179, v86, v54
	v_fma_f32 v175, -v102, v54, v175
	v_fmac_f32_e32 v179, v102, v22
	v_mul_f32_e32 v176, v87, v23
	v_mul_f32_e32 v180, v87, v55
	v_fma_f32 v176, -v103, v55, v176
	v_fmac_f32_e32 v180, v103, v23
	v_mul_f32_e32 v177, v88, v24
	v_mul_f32_e32 v181, v88, v56
	v_fma_f32 v177, -v104, v56, v177
	v_fmac_f32_e32 v181, v104, v24
	v_mul_f32_e32 v178, v89, v25
	v_mul_f32_e32 v182, v89, v57
	v_fma_f32 v178, -v105, v57, v178
	v_fmac_f32_e32 v182, v105, v25
	v_fmac_f32_e32 v175, v90, v26
	v_fmac_f32_e32 v179, v90, v58
	v_fma_f32 v175, -v106, v58, v175
	v_fmac_f32_e32 v179, v106, v26
	v_fmac_f32_e32 v176, v91, v27
	v_fmac_f32_e32 v180, v91, v59
	v_fma_f32 v176, -v107, v59, v176
	v_fmac_f32_e32 v180, v107, v27
	v_fmac_f32_e32 v177, v92, v28
	v_fmac_f32_e32 v181, v92, v60
	v_fma_f32 v177, -v108, v60, v177
	v_fmac_f32_e32 v181, v108, v28
	v_fmac_f32_e32 v178, v93, v29
	v_fmac_f32_e32 v182, v93, v61
	v_fma_f32 v178, -v109, v61, v178
	v_fmac_f32_e32 v182, v109, v29
	v_fmac_f32_e32 v175, v94, v30
	v_fmac_f32_e32 v179, v94, v62
	v_fma_f32 v175, -v110, v62, v175
	v_fmac_f32_e32 v179, v110, v30
	v_fmac_f32_e32 v176, v95, v31
	v_fmac_f32_e32 v180, v95, v63
	v_fma_f32 v176, -v111, v63, v176
	v_fmac_f32_e32 v180, v111, v31
	v_fmac_f32_e32 v177, v96, v32
	v_fmac_f32_e32 v181, v96, v64
	v_fma_f32 v177, -v112, v64, v177
	v_fmac_f32_e32 v181, v112, v32
	v_fmac_f32_e32 v178, v97, v33
	v_fmac_f32_e32 v182, v97, v65
	v_fma_f32 v178, -v113, v65, v178
	v_fmac_f32_e32 v182, v113, v33
	v_fmac_f32_e32 v175, v98, v34
	v_fmac_f32_e32 v179, v98, v66
	v_fma_f32 v175, -v114, v66, v175
	v_fmac_f32_e32 v179, v114, v34
	v_fmac_f32_e32 v176, v99, v35
	v_fmac_f32_e32 v180, v99, v67
	v_fma_f32 v176, -v115, v67, v176
	v_fmac_f32_e32 v180, v115, v35
	v_fmac_f32_e32 v177, v100, v36
	v_fmac_f32_e32 v181, v100, v68
	v_fma_f32 v177, -v116, v68, v177
	v_fmac_f32_e32 v181, v116, v36
	v_fmac_f32_e32 v178, v101, v37
	v_fmac_f32_e32 v182, v101, v69
	v_fma_f32 v178, -v117, v69, v178
	v_fmac_f32_e32 v182, v117, v37
	s_waitcnt lgkmcnt(0)
	v_add_f32_e32 v211, v211, v215
	v_add_f32_e32 v212, v212, v216
	v_add_f32_e32 v213, v213, v217
	v_add_f32_e32 v214, v214, v218
	v_fma_f32 v219, -v168, v172, v211
	v_fma_f32 v220, v168, v171, v212
	v_fma_f32 v171, v167, v171, v219
	v_fma_f32 v172, v167, v172, v220
	v_fma_f32 v219, -v170, v174, v213
	v_fma_f32 v220, v170, v173, v214
	v_fma_f32 v173, v169, v173, v219
	v_fma_f32 v174, v169, v174, v220
	v_mul_f32_e32 v183, v118, v38
	v_mul_f32_e32 v187, v118, v70
	v_fma_f32 v183, -v134, v70, v183
	v_fmac_f32_e32 v187, v134, v38
	v_mul_f32_e32 v184, v119, v39
	v_mul_f32_e32 v188, v119, v71
	v_fma_f32 v184, -v135, v71, v184
	v_fmac_f32_e32 v188, v135, v39
	v_mul_f32_e32 v185, v120, v40
	v_mul_f32_e32 v189, v120, v72
	v_fma_f32 v185, -v136, v72, v185
	v_fmac_f32_e32 v189, v136, v40
	v_mul_f32_e32 v186, v121, v41
	v_mul_f32_e32 v190, v121, v73
	v_fma_f32 v186, -v137, v73, v186
	v_fmac_f32_e32 v190, v137, v41
	v_fmac_f32_e32 v183, v122, v42
	v_fmac_f32_e32 v187, v122, v74
	v_fma_f32 v183, -v138, v74, v183
	v_fmac_f32_e32 v187, v138, v42
	v_fmac_f32_e32 v184, v123, v43
	v_fmac_f32_e32 v188, v123, v75
	v_fma_f32 v184, -v139, v75, v184
	v_fmac_f32_e32 v188, v139, v43
	v_fmac_f32_e32 v185, v124, v44
	v_fmac_f32_e32 v189, v124, v76
	v_fma_f32 v185, -v140, v76, v185
	v_fmac_f32_e32 v189, v140, v44
	v_fmac_f32_e32 v186, v125, v45
	v_fmac_f32_e32 v190, v125, v77
	v_fma_f32 v186, -v141, v77, v186
	v_fmac_f32_e32 v190, v141, v45
	v_fmac_f32_e32 v183, v126, v46
	v_fmac_f32_e32 v187, v126, v78
	v_fma_f32 v183, -v142, v78, v183
	v_fmac_f32_e32 v187, v142, v46
	v_fmac_f32_e32 v184, v127, v47
	v_fmac_f32_e32 v188, v127, v79
	v_fma_f32 v184, -v143, v79, v184
	v_fmac_f32_e32 v188, v143, v47
	v_fmac_f32_e32 v185, v128, v48
	v_fmac_f32_e32 v189, v128, v80
	v_fma_f32 v185, -v144, v80, v185
	v_fmac_f32_e32 v189, v144, v48
	v_fmac_f32_e32 v186, v129, v49
	v_fmac_f32_e32 v190, v129, v81
	v_fma_f32 v186, -v145, v81, v186
	v_fmac_f32_e32 v190, v145, v49
	v_fmac_f32_e32 v183, v130, v50
	v_fmac_f32_e32 v187, v130, v82
	v_fma_f32 v183, -v146, v82, v183
	v_fmac_f32_e32 v187, v146, v50
	v_fmac_f32_e32 v184, v131, v51
	v_fmac_f32_e32 v188, v131, v83
	v_fma_f32 v184, -v147, v83, v184
	v_fmac_f32_e32 v188, v147, v51
	v_fmac_f32_e32 v185, v132, v52
	v_fmac_f32_e32 v189, v132, v84
	v_fma_f32 v185, -v148, v84, v185
	v_fmac_f32_e32 v189, v148, v52
	v_fmac_f32_e32 v186, v133, v53
	v_fmac_f32_e32 v190, v133, v85
	v_fma_f32 v186, -v149, v85, v186
	v_fmac_f32_e32 v190, v149, v53
	s_waitcnt vmcnt(3)
	v_mfma_f32_32x32x16_bf16 v[22:37], v[204:207], v[6:9], 0
	v_mfma_f32_32x32x16_bf16 v[54:69], v[204:207], v[14:17], 0
	v_mfma_f32_32x32x16_bf16 v[38:53], v[204:207], v[10:13], 0
	v_mfma_f32_32x32x16_bf16 v[70:85], v[204:207], v[18:21], 0
	s_add_u32 s42, s32, 0xe0000
	s_addc_u32 s43, s33, 0
	global_load_dwordx4 v[204:207], v210, s[42:43]
	v_add_f32_e32 v219, v175, v176
	v_add_f32_e32 v220, v177, v178
	v_add_f32_e32 v211, v219, v220
	v_add_f32_e32 v219, v179, v180
	v_add_f32_e32 v220, v181, v182
	v_add_f32_e32 v212, v219, v220
	v_add_f32_e32 v219, v183, v184
	v_add_f32_e32 v220, v185, v186
	v_add_f32_e32 v213, v219, v220
	v_add_f32_e32 v219, v187, v188
	v_add_f32_e32 v220, v189, v190
	v_add_f32_e32 v214, v219, v220
	ds_bpermute_b32 v215, v208, v211
	ds_bpermute_b32 v216, v208, v212
	ds_bpermute_b32 v217, v208, v213
	ds_bpermute_b32 v218, v208, v214
	v_mul_f32_e32 v175, v86, v22
	v_mul_f32_e32 v179, v86, v54
	v_fma_f32 v175, -v102, v54, v175
	v_fmac_f32_e32 v179, v102, v22
	v_mul_f32_e32 v176, v87, v23
	v_mul_f32_e32 v180, v87, v55
	v_fma_f32 v176, -v103, v55, v176
	v_fmac_f32_e32 v180, v103, v23
	v_mul_f32_e32 v177, v88, v24
	v_mul_f32_e32 v181, v88, v56
	v_fma_f32 v177, -v104, v56, v177
	v_fmac_f32_e32 v181, v104, v24
	v_mul_f32_e32 v178, v89, v25
	v_mul_f32_e32 v182, v89, v57
	v_fma_f32 v178, -v105, v57, v178
	v_fmac_f32_e32 v182, v105, v25
	v_fmac_f32_e32 v175, v90, v26
	v_fmac_f32_e32 v179, v90, v58
	v_fma_f32 v175, -v106, v58, v175
	v_fmac_f32_e32 v179, v106, v26
	v_fmac_f32_e32 v176, v91, v27
	v_fmac_f32_e32 v180, v91, v59
	v_fma_f32 v176, -v107, v59, v176
	v_fmac_f32_e32 v180, v107, v27
	v_fmac_f32_e32 v177, v92, v28
	v_fmac_f32_e32 v181, v92, v60
	v_fma_f32 v177, -v108, v60, v177
	v_fmac_f32_e32 v181, v108, v28
	v_fmac_f32_e32 v178, v93, v29
	v_fmac_f32_e32 v182, v93, v61
	v_fma_f32 v178, -v109, v61, v178
	v_fmac_f32_e32 v182, v109, v29
	v_fmac_f32_e32 v175, v94, v30
	v_fmac_f32_e32 v179, v94, v62
	v_fma_f32 v175, -v110, v62, v175
	v_fmac_f32_e32 v179, v110, v30
	v_fmac_f32_e32 v176, v95, v31
	v_fmac_f32_e32 v180, v95, v63
	v_fma_f32 v176, -v111, v63, v176
	v_fmac_f32_e32 v180, v111, v31
	v_fmac_f32_e32 v177, v96, v32
	v_fmac_f32_e32 v181, v96, v64
	v_fma_f32 v177, -v112, v64, v177
	v_fmac_f32_e32 v181, v112, v32
	v_fmac_f32_e32 v178, v97, v33
	v_fmac_f32_e32 v182, v97, v65
	v_fma_f32 v178, -v113, v65, v178
	v_fmac_f32_e32 v182, v113, v33
	v_fmac_f32_e32 v175, v98, v34
	v_fmac_f32_e32 v179, v98, v66
	v_fma_f32 v175, -v114, v66, v175
	v_fmac_f32_e32 v179, v114, v34
	v_fmac_f32_e32 v176, v99, v35
	v_fmac_f32_e32 v180, v99, v67
	v_fma_f32 v176, -v115, v67, v176
	v_fmac_f32_e32 v180, v115, v35
	v_fmac_f32_e32 v177, v100, v36
	v_fmac_f32_e32 v181, v100, v68
	v_fma_f32 v177, -v116, v68, v177
	v_fmac_f32_e32 v181, v116, v36
	v_fmac_f32_e32 v178, v101, v37
	v_fmac_f32_e32 v182, v101, v69
	v_fma_f32 v178, -v117, v69, v178
	v_fmac_f32_e32 v182, v117, v37
	s_waitcnt lgkmcnt(0)
	v_add_f32_e32 v211, v211, v215
	v_add_f32_e32 v212, v212, v216
	v_add_f32_e32 v213, v213, v217
	v_add_f32_e32 v214, v214, v218
	v_fma_f32 v219, -v168, v172, v211
	v_fma_f32 v220, v168, v171, v212
	v_fma_f32 v171, v167, v171, v219
	v_fma_f32 v172, v167, v172, v220
	v_fma_f32 v219, -v170, v174, v213
	v_fma_f32 v220, v170, v173, v214
	v_fma_f32 v173, v169, v173, v219
	v_fma_f32 v174, v169, v174, v220
	v_mul_f32_e32 v183, v118, v38
	v_mul_f32_e32 v187, v118, v70
	v_fma_f32 v183, -v134, v70, v183
	v_fmac_f32_e32 v187, v134, v38
	v_mul_f32_e32 v184, v119, v39
	v_mul_f32_e32 v188, v119, v71
	v_fma_f32 v184, -v135, v71, v184
	v_fmac_f32_e32 v188, v135, v39
	v_mul_f32_e32 v185, v120, v40
	v_mul_f32_e32 v189, v120, v72
	v_fma_f32 v185, -v136, v72, v185
	v_fmac_f32_e32 v189, v136, v40
	v_mul_f32_e32 v186, v121, v41
	v_mul_f32_e32 v190, v121, v73
	v_fma_f32 v186, -v137, v73, v186
	v_fmac_f32_e32 v190, v137, v41
	v_fmac_f32_e32 v183, v122, v42
	v_fmac_f32_e32 v187, v122, v74
	v_fma_f32 v183, -v138, v74, v183
	v_fmac_f32_e32 v187, v138, v42
	v_fmac_f32_e32 v184, v123, v43
	v_fmac_f32_e32 v188, v123, v75
	v_fma_f32 v184, -v139, v75, v184
	v_fmac_f32_e32 v188, v139, v43
	v_fmac_f32_e32 v185, v124, v44
	v_fmac_f32_e32 v189, v124, v76
	v_fma_f32 v185, -v140, v76, v185
	v_fmac_f32_e32 v189, v140, v44
	v_fmac_f32_e32 v186, v125, v45
	v_fmac_f32_e32 v190, v125, v77
	v_fma_f32 v186, -v141, v77, v186
	v_fmac_f32_e32 v190, v141, v45
	v_fmac_f32_e32 v183, v126, v46
	v_fmac_f32_e32 v187, v126, v78
	v_fma_f32 v183, -v142, v78, v183
	v_fmac_f32_e32 v187, v142, v46
	v_fmac_f32_e32 v184, v127, v47
	v_fmac_f32_e32 v188, v127, v79
	v_fma_f32 v184, -v143, v79, v184
	v_fmac_f32_e32 v188, v143, v47
	v_fmac_f32_e32 v185, v128, v48
	v_fmac_f32_e32 v189, v128, v80
	v_fma_f32 v185, -v144, v80, v185
	v_fmac_f32_e32 v189, v144, v48
	v_fmac_f32_e32 v186, v129, v49
	v_fmac_f32_e32 v190, v129, v81
	v_fma_f32 v186, -v145, v81, v186
	v_fmac_f32_e32 v190, v145, v49
	v_fmac_f32_e32 v183, v130, v50
	v_fmac_f32_e32 v187, v130, v82
	v_fma_f32 v183, -v146, v82, v183
	v_fmac_f32_e32 v187, v146, v50
	v_fmac_f32_e32 v184, v131, v51
	v_fmac_f32_e32 v188, v131, v83
	v_fma_f32 v184, -v147, v83, v184
	v_fmac_f32_e32 v188, v147, v51
	v_fmac_f32_e32 v185, v132, v52
	v_fmac_f32_e32 v189, v132, v84
	v_fma_f32 v185, -v148, v84, v185
	v_fmac_f32_e32 v189, v148, v52
	v_fmac_f32_e32 v186, v133, v53
	v_fmac_f32_e32 v190, v133, v85
	v_fma_f32 v186, -v149, v85, v186
	v_fmac_f32_e32 v190, v149, v53
	s_waitcnt vmcnt(3)
	v_mfma_f32_32x32x16_bf16 v[22:37], v[192:195], v[6:9], 0
	v_mfma_f32_32x32x16_bf16 v[54:69], v[192:195], v[14:17], 0
	v_mfma_f32_32x32x16_bf16 v[38:53], v[192:195], v[10:13], 0
	v_mfma_f32_32x32x16_bf16 v[70:85], v[192:195], v[18:21], 0
	s_add_u32 s42, s32, 0x100000
	s_addc_u32 s43, s33, 0
	global_load_dwordx4 v[192:195], v210, s[42:43]
	v_add_f32_e32 v219, v175, v176
	v_add_f32_e32 v220, v177, v178
	v_add_f32_e32 v211, v219, v220
	v_add_f32_e32 v219, v179, v180
	v_add_f32_e32 v220, v181, v182
	v_add_f32_e32 v212, v219, v220
	v_add_f32_e32 v219, v183, v184
	v_add_f32_e32 v220, v185, v186
	v_add_f32_e32 v213, v219, v220
	v_add_f32_e32 v219, v187, v188
	v_add_f32_e32 v220, v189, v190
	v_add_f32_e32 v214, v219, v220
	ds_bpermute_b32 v215, v208, v211
	ds_bpermute_b32 v216, v208, v212
	ds_bpermute_b32 v217, v208, v213
	ds_bpermute_b32 v218, v208, v214
	v_mul_f32_e32 v175, v86, v22
	v_mul_f32_e32 v179, v86, v54
	v_fma_f32 v175, -v102, v54, v175
	v_fmac_f32_e32 v179, v102, v22
	v_mul_f32_e32 v176, v87, v23
	v_mul_f32_e32 v180, v87, v55
	v_fma_f32 v176, -v103, v55, v176
	v_fmac_f32_e32 v180, v103, v23
	v_mul_f32_e32 v177, v88, v24
	v_mul_f32_e32 v181, v88, v56
	v_fma_f32 v177, -v104, v56, v177
	v_fmac_f32_e32 v181, v104, v24
	v_mul_f32_e32 v178, v89, v25
	v_mul_f32_e32 v182, v89, v57
	v_fma_f32 v178, -v105, v57, v178
	v_fmac_f32_e32 v182, v105, v25
	v_fmac_f32_e32 v175, v90, v26
	v_fmac_f32_e32 v179, v90, v58
	v_fma_f32 v175, -v106, v58, v175
	v_fmac_f32_e32 v179, v106, v26
	v_fmac_f32_e32 v176, v91, v27
	v_fmac_f32_e32 v180, v91, v59
	v_fma_f32 v176, -v107, v59, v176
	v_fmac_f32_e32 v180, v107, v27
	v_fmac_f32_e32 v177, v92, v28
	v_fmac_f32_e32 v181, v92, v60
	v_fma_f32 v177, -v108, v60, v177
	v_fmac_f32_e32 v181, v108, v28
	v_fmac_f32_e32 v178, v93, v29
	v_fmac_f32_e32 v182, v93, v61
	v_fma_f32 v178, -v109, v61, v178
	v_fmac_f32_e32 v182, v109, v29
	v_fmac_f32_e32 v175, v94, v30
	v_fmac_f32_e32 v179, v94, v62
	v_fma_f32 v175, -v110, v62, v175
	v_fmac_f32_e32 v179, v110, v30
	v_fmac_f32_e32 v176, v95, v31
	v_fmac_f32_e32 v180, v95, v63
	v_fma_f32 v176, -v111, v63, v176
	v_fmac_f32_e32 v180, v111, v31
	v_fmac_f32_e32 v177, v96, v32
	v_fmac_f32_e32 v181, v96, v64
	v_fma_f32 v177, -v112, v64, v177
	v_fmac_f32_e32 v181, v112, v32
	v_fmac_f32_e32 v178, v97, v33
	v_fmac_f32_e32 v182, v97, v65
	v_fma_f32 v178, -v113, v65, v178
	v_fmac_f32_e32 v182, v113, v33
	v_fmac_f32_e32 v175, v98, v34
	v_fmac_f32_e32 v179, v98, v66
	v_fma_f32 v175, -v114, v66, v175
	v_fmac_f32_e32 v179, v114, v34
	v_fmac_f32_e32 v176, v99, v35
	v_fmac_f32_e32 v180, v99, v67
	v_fma_f32 v176, -v115, v67, v176
	v_fmac_f32_e32 v180, v115, v35
	v_fmac_f32_e32 v177, v100, v36
	v_fmac_f32_e32 v181, v100, v68
	v_fma_f32 v177, -v116, v68, v177
	v_fmac_f32_e32 v181, v116, v36
	v_fmac_f32_e32 v178, v101, v37
	v_fmac_f32_e32 v182, v101, v69
	v_fma_f32 v178, -v117, v69, v178
	v_fmac_f32_e32 v182, v117, v37
	s_waitcnt lgkmcnt(0)
	v_add_f32_e32 v211, v211, v215
	v_add_f32_e32 v212, v212, v216
	v_add_f32_e32 v213, v213, v217
	v_add_f32_e32 v214, v214, v218
	v_fma_f32 v219, -v168, v172, v211
	v_fma_f32 v220, v168, v171, v212
	v_fma_f32 v171, v167, v171, v219
	v_fma_f32 v172, v167, v172, v220
	v_fma_f32 v219, -v170, v174, v213
	v_fma_f32 v220, v170, v173, v214
	v_fma_f32 v173, v169, v173, v219
	v_fma_f32 v174, v169, v174, v220
	s_add_u32 s42, s38, 0x0
	s_addc_u32 s43, s39, 0
	s_mov_b64 exec, s[12:13]
	global_store_dword v209, v171, s[42:43]
	global_store_dword v209, v172, s[42:43] offset:256
	global_store_dword v209, v173, s[42:43] offset:128
	global_store_dword v209, v174, s[42:43] offset:384
	s_mov_b64 exec, -1
	v_mul_f32_e32 v183, v118, v38
	v_mul_f32_e32 v187, v118, v70
	v_fma_f32 v183, -v134, v70, v183
	v_fmac_f32_e32 v187, v134, v38
	v_mul_f32_e32 v184, v119, v39
	v_mul_f32_e32 v188, v119, v71
	v_fma_f32 v184, -v135, v71, v184
	v_fmac_f32_e32 v188, v135, v39
	v_mul_f32_e32 v185, v120, v40
	v_mul_f32_e32 v189, v120, v72
	v_fma_f32 v185, -v136, v72, v185
	v_fmac_f32_e32 v189, v136, v40
	v_mul_f32_e32 v186, v121, v41
	v_mul_f32_e32 v190, v121, v73
	v_fma_f32 v186, -v137, v73, v186
	v_fmac_f32_e32 v190, v137, v41
	v_fmac_f32_e32 v183, v122, v42
	v_fmac_f32_e32 v187, v122, v74
	v_fma_f32 v183, -v138, v74, v183
	v_fmac_f32_e32 v187, v138, v42
	v_fmac_f32_e32 v184, v123, v43
	v_fmac_f32_e32 v188, v123, v75
	v_fma_f32 v184, -v139, v75, v184
	v_fmac_f32_e32 v188, v139, v43
	v_fmac_f32_e32 v185, v124, v44
	v_fmac_f32_e32 v189, v124, v76
	v_fma_f32 v185, -v140, v76, v185
	v_fmac_f32_e32 v189, v140, v44
	v_fmac_f32_e32 v186, v125, v45
	v_fmac_f32_e32 v190, v125, v77
	v_fma_f32 v186, -v141, v77, v186
	v_fmac_f32_e32 v190, v141, v45
	v_fmac_f32_e32 v183, v126, v46
	v_fmac_f32_e32 v187, v126, v78
	v_fma_f32 v183, -v142, v78, v183
	v_fmac_f32_e32 v187, v142, v46
	v_fmac_f32_e32 v184, v127, v47
	v_fmac_f32_e32 v188, v127, v79
	v_fma_f32 v184, -v143, v79, v184
	v_fmac_f32_e32 v188, v143, v47
	v_fmac_f32_e32 v185, v128, v48
	v_fmac_f32_e32 v189, v128, v80
	v_fma_f32 v185, -v144, v80, v185
	v_fmac_f32_e32 v189, v144, v48
	v_fmac_f32_e32 v186, v129, v49
	v_fmac_f32_e32 v190, v129, v81
	v_fma_f32 v186, -v145, v81, v186
	v_fmac_f32_e32 v190, v145, v49
	v_fmac_f32_e32 v183, v130, v50
	v_fmac_f32_e32 v187, v130, v82
	v_fma_f32 v183, -v146, v82, v183
	v_fmac_f32_e32 v187, v146, v50
	v_fmac_f32_e32 v184, v131, v51
	v_fmac_f32_e32 v188, v131, v83
	v_fma_f32 v184, -v147, v83, v184
	v_fmac_f32_e32 v188, v147, v51
	v_fmac_f32_e32 v185, v132, v52
	v_fmac_f32_e32 v189, v132, v84
	v_fma_f32 v185, -v148, v84, v185
	v_fmac_f32_e32 v189, v148, v52
	v_fmac_f32_e32 v186, v133, v53
	v_fmac_f32_e32 v190, v133, v85
	v_fma_f32 v186, -v149, v85, v186
	v_fmac_f32_e32 v190, v149, v53
	s_waitcnt vmcnt(7)
	v_mfma_f32_32x32x16_bf16 v[22:37], v[196:199], v[6:9], 0
	v_mfma_f32_32x32x16_bf16 v[54:69], v[196:199], v[14:17], 0
	v_mfma_f32_32x32x16_bf16 v[38:53], v[196:199], v[10:13], 0
	v_mfma_f32_32x32x16_bf16 v[70:85], v[196:199], v[18:21], 0
	s_add_u32 s42, s32, 0x120000
	s_addc_u32 s43, s33, 0
	global_load_dwordx4 v[196:199], v210, s[42:43]
	v_add_f32_e32 v219, v175, v176
	v_add_f32_e32 v220, v177, v178
	v_add_f32_e32 v211, v219, v220
	v_add_f32_e32 v219, v179, v180
	v_add_f32_e32 v220, v181, v182
	v_add_f32_e32 v212, v219, v220
	v_add_f32_e32 v219, v183, v184
	v_add_f32_e32 v220, v185, v186
	v_add_f32_e32 v213, v219, v220
	v_add_f32_e32 v219, v187, v188
	v_add_f32_e32 v220, v189, v190
	v_add_f32_e32 v214, v219, v220
	ds_bpermute_b32 v215, v208, v211
	ds_bpermute_b32 v216, v208, v212
	ds_bpermute_b32 v217, v208, v213
	ds_bpermute_b32 v218, v208, v214
	v_mul_f32_e32 v175, v86, v22
	v_mul_f32_e32 v179, v86, v54
	v_fma_f32 v175, -v102, v54, v175
	v_fmac_f32_e32 v179, v102, v22
	v_mul_f32_e32 v176, v87, v23
	v_mul_f32_e32 v180, v87, v55
	v_fma_f32 v176, -v103, v55, v176
	v_fmac_f32_e32 v180, v103, v23
	v_mul_f32_e32 v177, v88, v24
	v_mul_f32_e32 v181, v88, v56
	v_fma_f32 v177, -v104, v56, v177
	v_fmac_f32_e32 v181, v104, v24
	v_mul_f32_e32 v178, v89, v25
	v_mul_f32_e32 v182, v89, v57
	v_fma_f32 v178, -v105, v57, v178
	v_fmac_f32_e32 v182, v105, v25
	v_fmac_f32_e32 v175, v90, v26
	v_fmac_f32_e32 v179, v90, v58
	v_fma_f32 v175, -v106, v58, v175
	v_fmac_f32_e32 v179, v106, v26
	v_fmac_f32_e32 v176, v91, v27
	v_fmac_f32_e32 v180, v91, v59
	v_fma_f32 v176, -v107, v59, v176
	v_fmac_f32_e32 v180, v107, v27
	v_fmac_f32_e32 v177, v92, v28
	v_fmac_f32_e32 v181, v92, v60
	v_fma_f32 v177, -v108, v60, v177
	v_fmac_f32_e32 v181, v108, v28
	v_fmac_f32_e32 v178, v93, v29
	v_fmac_f32_e32 v182, v93, v61
	v_fma_f32 v178, -v109, v61, v178
	v_fmac_f32_e32 v182, v109, v29
	v_fmac_f32_e32 v175, v94, v30
	v_fmac_f32_e32 v179, v94, v62
	v_fma_f32 v175, -v110, v62, v175
	v_fmac_f32_e32 v179, v110, v30
	v_fmac_f32_e32 v176, v95, v31
	v_fmac_f32_e32 v180, v95, v63
	v_fma_f32 v176, -v111, v63, v176
	v_fmac_f32_e32 v180, v111, v31
	v_fmac_f32_e32 v177, v96, v32
	v_fmac_f32_e32 v181, v96, v64
	v_fma_f32 v177, -v112, v64, v177
	v_fmac_f32_e32 v181, v112, v32
	v_fmac_f32_e32 v178, v97, v33
	v_fmac_f32_e32 v182, v97, v65
	v_fma_f32 v178, -v113, v65, v178
	v_fmac_f32_e32 v182, v113, v33
	v_fmac_f32_e32 v175, v98, v34
	v_fmac_f32_e32 v179, v98, v66
	v_fma_f32 v175, -v114, v66, v175
	v_fmac_f32_e32 v179, v114, v34
	v_fmac_f32_e32 v176, v99, v35
	v_fmac_f32_e32 v180, v99, v67
	v_fma_f32 v176, -v115, v67, v176
	v_fmac_f32_e32 v180, v115, v35
	v_fmac_f32_e32 v177, v100, v36
	v_fmac_f32_e32 v181, v100, v68
	v_fma_f32 v177, -v116, v68, v177
	v_fmac_f32_e32 v181, v116, v36
	v_fmac_f32_e32 v178, v101, v37
	v_fmac_f32_e32 v182, v101, v69
	v_fma_f32 v178, -v117, v69, v178
	v_fmac_f32_e32 v182, v117, v37
	s_waitcnt lgkmcnt(0)
	v_add_f32_e32 v211, v211, v215
	v_add_f32_e32 v212, v212, v216
	v_add_f32_e32 v213, v213, v217
	v_add_f32_e32 v214, v214, v218
	v_fma_f32 v219, -v168, v172, v211
	v_fma_f32 v220, v168, v171, v212
	v_fma_f32 v171, v167, v171, v219
	v_fma_f32 v172, v167, v172, v220
	v_fma_f32 v219, -v170, v174, v213
	v_fma_f32 v220, v170, v173, v214
	v_fma_f32 v173, v169, v173, v219
	v_fma_f32 v174, v169, v174, v220
	v_mul_f32_e32 v183, v118, v38
	v_mul_f32_e32 v187, v118, v70
	v_fma_f32 v183, -v134, v70, v183
	v_fmac_f32_e32 v187, v134, v38
	v_mul_f32_e32 v184, v119, v39
	v_mul_f32_e32 v188, v119, v71
	v_fma_f32 v184, -v135, v71, v184
	v_fmac_f32_e32 v188, v135, v39
	v_mul_f32_e32 v185, v120, v40
	v_mul_f32_e32 v189, v120, v72
	v_fma_f32 v185, -v136, v72, v185
	v_fmac_f32_e32 v189, v136, v40
	v_mul_f32_e32 v186, v121, v41
	v_mul_f32_e32 v190, v121, v73
	v_fma_f32 v186, -v137, v73, v186
	v_fmac_f32_e32 v190, v137, v41
	v_fmac_f32_e32 v183, v122, v42
	v_fmac_f32_e32 v187, v122, v74
	v_fma_f32 v183, -v138, v74, v183
	v_fmac_f32_e32 v187, v138, v42
	v_fmac_f32_e32 v184, v123, v43
	v_fmac_f32_e32 v188, v123, v75
	v_fma_f32 v184, -v139, v75, v184
	v_fmac_f32_e32 v188, v139, v43
	v_fmac_f32_e32 v185, v124, v44
	v_fmac_f32_e32 v189, v124, v76
	v_fma_f32 v185, -v140, v76, v185
	v_fmac_f32_e32 v189, v140, v44
	v_fmac_f32_e32 v186, v125, v45
	v_fmac_f32_e32 v190, v125, v77
	v_fma_f32 v186, -v141, v77, v186
	v_fmac_f32_e32 v190, v141, v45
	v_fmac_f32_e32 v183, v126, v46
	v_fmac_f32_e32 v187, v126, v78
	v_fma_f32 v183, -v142, v78, v183
	v_fmac_f32_e32 v187, v142, v46
	v_fmac_f32_e32 v184, v127, v47
	v_fmac_f32_e32 v188, v127, v79
	v_fma_f32 v184, -v143, v79, v184
	v_fmac_f32_e32 v188, v143, v47
	v_fmac_f32_e32 v185, v128, v48
	v_fmac_f32_e32 v189, v128, v80
	v_fma_f32 v185, -v144, v80, v185
	v_fmac_f32_e32 v189, v144, v48
	v_fmac_f32_e32 v186, v129, v49
	v_fmac_f32_e32 v190, v129, v81
	v_fma_f32 v186, -v145, v81, v186
	v_fmac_f32_e32 v190, v145, v49
	v_fmac_f32_e32 v183, v130, v50
	v_fmac_f32_e32 v187, v130, v82
	v_fma_f32 v183, -v146, v82, v183
	v_fmac_f32_e32 v187, v146, v50
	v_fmac_f32_e32 v184, v131, v51
	v_fmac_f32_e32 v188, v131, v83
	v_fma_f32 v184, -v147, v83, v184
	v_fmac_f32_e32 v188, v147, v51
	v_fmac_f32_e32 v185, v132, v52
	v_fmac_f32_e32 v189, v132, v84
	v_fma_f32 v185, -v148, v84, v185
	v_fmac_f32_e32 v189, v148, v52
	v_fmac_f32_e32 v186, v133, v53
	v_fmac_f32_e32 v190, v133, v85
	v_fma_f32 v186, -v149, v85, v186
	v_fmac_f32_e32 v190, v149, v53
	s_waitcnt vmcnt(7)
	v_mfma_f32_32x32x16_bf16 v[22:37], v[200:203], v[6:9], 0
	v_mfma_f32_32x32x16_bf16 v[54:69], v[200:203], v[14:17], 0
	v_mfma_f32_32x32x16_bf16 v[38:53], v[200:203], v[10:13], 0
	v_mfma_f32_32x32x16_bf16 v[70:85], v[200:203], v[18:21], 0
	s_add_u32 s42, s32, 0x140000
	s_addc_u32 s43, s33, 0
	global_load_dwordx4 v[200:203], v210, s[42:43]
	v_add_f32_e32 v219, v175, v176
	v_add_f32_e32 v220, v177, v178
	v_add_f32_e32 v211, v219, v220
	v_add_f32_e32 v219, v179, v180
	v_add_f32_e32 v220, v181, v182
	v_add_f32_e32 v212, v219, v220
	v_add_f32_e32 v219, v183, v184
	v_add_f32_e32 v220, v185, v186
	v_add_f32_e32 v213, v219, v220
	v_add_f32_e32 v219, v187, v188
	v_add_f32_e32 v220, v189, v190
	v_add_f32_e32 v214, v219, v220
	ds_bpermute_b32 v215, v208, v211
	ds_bpermute_b32 v216, v208, v212
	ds_bpermute_b32 v217, v208, v213
	ds_bpermute_b32 v218, v208, v214
	v_mul_f32_e32 v175, v86, v22
	v_mul_f32_e32 v179, v86, v54
	v_fma_f32 v175, -v102, v54, v175
	v_fmac_f32_e32 v179, v102, v22
	v_mul_f32_e32 v176, v87, v23
	v_mul_f32_e32 v180, v87, v55
	v_fma_f32 v176, -v103, v55, v176
	v_fmac_f32_e32 v180, v103, v23
	v_mul_f32_e32 v177, v88, v24
	v_mul_f32_e32 v181, v88, v56
	v_fma_f32 v177, -v104, v56, v177
	v_fmac_f32_e32 v181, v104, v24
	v_mul_f32_e32 v178, v89, v25
	v_mul_f32_e32 v182, v89, v57
	v_fma_f32 v178, -v105, v57, v178
	v_fmac_f32_e32 v182, v105, v25
	v_fmac_f32_e32 v175, v90, v26
	v_fmac_f32_e32 v179, v90, v58
	v_fma_f32 v175, -v106, v58, v175
	v_fmac_f32_e32 v179, v106, v26
	v_fmac_f32_e32 v176, v91, v27
	v_fmac_f32_e32 v180, v91, v59
	v_fma_f32 v176, -v107, v59, v176
	v_fmac_f32_e32 v180, v107, v27
	v_fmac_f32_e32 v177, v92, v28
	v_fmac_f32_e32 v181, v92, v60
	v_fma_f32 v177, -v108, v60, v177
	v_fmac_f32_e32 v181, v108, v28
	v_fmac_f32_e32 v178, v93, v29
	v_fmac_f32_e32 v182, v93, v61
	v_fma_f32 v178, -v109, v61, v178
	v_fmac_f32_e32 v182, v109, v29
	v_fmac_f32_e32 v175, v94, v30
	v_fmac_f32_e32 v179, v94, v62
	v_fma_f32 v175, -v110, v62, v175
	v_fmac_f32_e32 v179, v110, v30
	v_fmac_f32_e32 v176, v95, v31
	v_fmac_f32_e32 v180, v95, v63
	v_fma_f32 v176, -v111, v63, v176
	v_fmac_f32_e32 v180, v111, v31
	v_fmac_f32_e32 v177, v96, v32
	v_fmac_f32_e32 v181, v96, v64
	v_fma_f32 v177, -v112, v64, v177
	v_fmac_f32_e32 v181, v112, v32
	v_fmac_f32_e32 v178, v97, v33
	v_fmac_f32_e32 v182, v97, v65
	v_fma_f32 v178, -v113, v65, v178
	v_fmac_f32_e32 v182, v113, v33
	v_fmac_f32_e32 v175, v98, v34
	v_fmac_f32_e32 v179, v98, v66
	v_fma_f32 v175, -v114, v66, v175
	v_fmac_f32_e32 v179, v114, v34
	v_fmac_f32_e32 v176, v99, v35
	v_fmac_f32_e32 v180, v99, v67
	v_fma_f32 v176, -v115, v67, v176
	v_fmac_f32_e32 v180, v115, v35
	v_fmac_f32_e32 v177, v100, v36
	v_fmac_f32_e32 v181, v100, v68
	v_fma_f32 v177, -v116, v68, v177
	v_fmac_f32_e32 v181, v116, v36
	v_fmac_f32_e32 v178, v101, v37
	v_fmac_f32_e32 v182, v101, v69
	v_fma_f32 v178, -v117, v69, v178
	v_fmac_f32_e32 v182, v117, v37
	s_waitcnt lgkmcnt(0)
	v_add_f32_e32 v211, v211, v215
	v_add_f32_e32 v212, v212, v216
	v_add_f32_e32 v213, v213, v217
	v_add_f32_e32 v214, v214, v218
	v_fma_f32 v219, -v168, v172, v211
	v_fma_f32 v220, v168, v171, v212
	v_fma_f32 v171, v167, v171, v219
	v_fma_f32 v172, v167, v172, v220
	v_fma_f32 v219, -v170, v174, v213
	v_fma_f32 v220, v170, v173, v214
	v_fma_f32 v173, v169, v173, v219
	v_fma_f32 v174, v169, v174, v220
	v_mul_f32_e32 v183, v118, v38
	v_mul_f32_e32 v187, v118, v70
	v_fma_f32 v183, -v134, v70, v183
	v_fmac_f32_e32 v187, v134, v38
	v_mul_f32_e32 v184, v119, v39
	v_mul_f32_e32 v188, v119, v71
	v_fma_f32 v184, -v135, v71, v184
	v_fmac_f32_e32 v188, v135, v39
	v_mul_f32_e32 v185, v120, v40
	v_mul_f32_e32 v189, v120, v72
	v_fma_f32 v185, -v136, v72, v185
	v_fmac_f32_e32 v189, v136, v40
	v_mul_f32_e32 v186, v121, v41
	v_mul_f32_e32 v190, v121, v73
	v_fma_f32 v186, -v137, v73, v186
	v_fmac_f32_e32 v190, v137, v41
	v_fmac_f32_e32 v183, v122, v42
	v_fmac_f32_e32 v187, v122, v74
	v_fma_f32 v183, -v138, v74, v183
	v_fmac_f32_e32 v187, v138, v42
	v_fmac_f32_e32 v184, v123, v43
	v_fmac_f32_e32 v188, v123, v75
	v_fma_f32 v184, -v139, v75, v184
	v_fmac_f32_e32 v188, v139, v43
	v_fmac_f32_e32 v185, v124, v44
	v_fmac_f32_e32 v189, v124, v76
	v_fma_f32 v185, -v140, v76, v185
	v_fmac_f32_e32 v189, v140, v44
	v_fmac_f32_e32 v186, v125, v45
	v_fmac_f32_e32 v190, v125, v77
	v_fma_f32 v186, -v141, v77, v186
	v_fmac_f32_e32 v190, v141, v45
	v_fmac_f32_e32 v183, v126, v46
	v_fmac_f32_e32 v187, v126, v78
	v_fma_f32 v183, -v142, v78, v183
	v_fmac_f32_e32 v187, v142, v46
	v_fmac_f32_e32 v184, v127, v47
	v_fmac_f32_e32 v188, v127, v79
	v_fma_f32 v184, -v143, v79, v184
	v_fmac_f32_e32 v188, v143, v47
	v_fmac_f32_e32 v185, v128, v48
	v_fmac_f32_e32 v189, v128, v80
	v_fma_f32 v185, -v144, v80, v185
	v_fmac_f32_e32 v189, v144, v48
	v_fmac_f32_e32 v186, v129, v49
	v_fmac_f32_e32 v190, v129, v81
	v_fma_f32 v186, -v145, v81, v186
	v_fmac_f32_e32 v190, v145, v49
	v_fmac_f32_e32 v183, v130, v50
	v_fmac_f32_e32 v187, v130, v82
	v_fma_f32 v183, -v146, v82, v183
	v_fmac_f32_e32 v187, v146, v50
	v_fmac_f32_e32 v184, v131, v51
	v_fmac_f32_e32 v188, v131, v83
	v_fma_f32 v184, -v147, v83, v184
	v_fmac_f32_e32 v188, v147, v51
	v_fmac_f32_e32 v185, v132, v52
	v_fmac_f32_e32 v189, v132, v84
	v_fma_f32 v185, -v148, v84, v185
	v_fmac_f32_e32 v189, v148, v52
	v_fmac_f32_e32 v186, v133, v53
	v_fmac_f32_e32 v190, v133, v85
	v_fma_f32 v186, -v149, v85, v186
	v_fmac_f32_e32 v190, v149, v53
	s_waitcnt vmcnt(7)
	v_mfma_f32_32x32x16_bf16 v[22:37], v[204:207], v[6:9], 0
	v_mfma_f32_32x32x16_bf16 v[54:69], v[204:207], v[14:17], 0
	v_mfma_f32_32x32x16_bf16 v[38:53], v[204:207], v[10:13], 0
	v_mfma_f32_32x32x16_bf16 v[70:85], v[204:207], v[18:21], 0
	s_add_u32 s42, s32, 0x160000
	s_addc_u32 s43, s33, 0
	global_load_dwordx4 v[204:207], v210, s[42:43]
	v_add_f32_e32 v219, v175, v176
	v_add_f32_e32 v220, v177, v178
	v_add_f32_e32 v211, v219, v220
	v_add_f32_e32 v219, v179, v180
	v_add_f32_e32 v220, v181, v182
	v_add_f32_e32 v212, v219, v220
	v_add_f32_e32 v219, v183, v184
	v_add_f32_e32 v220, v185, v186
	v_add_f32_e32 v213, v219, v220
	v_add_f32_e32 v219, v187, v188
	v_add_f32_e32 v220, v189, v190
	v_add_f32_e32 v214, v219, v220
	ds_bpermute_b32 v215, v208, v211
	ds_bpermute_b32 v216, v208, v212
	ds_bpermute_b32 v217, v208, v213
	ds_bpermute_b32 v218, v208, v214
	v_mul_f32_e32 v175, v86, v22
	v_mul_f32_e32 v179, v86, v54
	v_fma_f32 v175, -v102, v54, v175
	v_fmac_f32_e32 v179, v102, v22
	v_mul_f32_e32 v176, v87, v23
	v_mul_f32_e32 v180, v87, v55
	v_fma_f32 v176, -v103, v55, v176
	v_fmac_f32_e32 v180, v103, v23
	v_mul_f32_e32 v177, v88, v24
	v_mul_f32_e32 v181, v88, v56
	v_fma_f32 v177, -v104, v56, v177
	v_fmac_f32_e32 v181, v104, v24
	v_mul_f32_e32 v178, v89, v25
	v_mul_f32_e32 v182, v89, v57
	v_fma_f32 v178, -v105, v57, v178
	v_fmac_f32_e32 v182, v105, v25
	v_fmac_f32_e32 v175, v90, v26
	v_fmac_f32_e32 v179, v90, v58
	v_fma_f32 v175, -v106, v58, v175
	v_fmac_f32_e32 v179, v106, v26
	v_fmac_f32_e32 v176, v91, v27
	v_fmac_f32_e32 v180, v91, v59
	v_fma_f32 v176, -v107, v59, v176
	v_fmac_f32_e32 v180, v107, v27
	v_fmac_f32_e32 v177, v92, v28
	v_fmac_f32_e32 v181, v92, v60
	v_fma_f32 v177, -v108, v60, v177
	v_fmac_f32_e32 v181, v108, v28
	v_fmac_f32_e32 v178, v93, v29
	v_fmac_f32_e32 v182, v93, v61
	v_fma_f32 v178, -v109, v61, v178
	v_fmac_f32_e32 v182, v109, v29
	v_fmac_f32_e32 v175, v94, v30
	v_fmac_f32_e32 v179, v94, v62
	v_fma_f32 v175, -v110, v62, v175
	v_fmac_f32_e32 v179, v110, v30
	v_fmac_f32_e32 v176, v95, v31
	v_fmac_f32_e32 v180, v95, v63
	v_fma_f32 v176, -v111, v63, v176
	v_fmac_f32_e32 v180, v111, v31
	v_fmac_f32_e32 v177, v96, v32
	v_fmac_f32_e32 v181, v96, v64
	v_fma_f32 v177, -v112, v64, v177
	v_fmac_f32_e32 v181, v112, v32
	v_fmac_f32_e32 v178, v97, v33
	v_fmac_f32_e32 v182, v97, v65
	v_fma_f32 v178, -v113, v65, v178
	v_fmac_f32_e32 v182, v113, v33
	v_fmac_f32_e32 v175, v98, v34
	v_fmac_f32_e32 v179, v98, v66
	v_fma_f32 v175, -v114, v66, v175
	v_fmac_f32_e32 v179, v114, v34
	v_fmac_f32_e32 v176, v99, v35
	v_fmac_f32_e32 v180, v99, v67
	v_fma_f32 v176, -v115, v67, v176
	v_fmac_f32_e32 v180, v115, v35
	v_fmac_f32_e32 v177, v100, v36
	v_fmac_f32_e32 v181, v100, v68
	v_fma_f32 v177, -v116, v68, v177
	v_fmac_f32_e32 v181, v116, v36
	v_fmac_f32_e32 v178, v101, v37
	v_fmac_f32_e32 v182, v101, v69
	v_fma_f32 v178, -v117, v69, v178
	v_fmac_f32_e32 v182, v117, v37
	s_waitcnt lgkmcnt(0)
	v_add_f32_e32 v211, v211, v215
	v_add_f32_e32 v212, v212, v216
	v_add_f32_e32 v213, v213, v217
	v_add_f32_e32 v214, v214, v218
	v_fma_f32 v219, -v168, v172, v211
	v_fma_f32 v220, v168, v171, v212
	v_fma_f32 v171, v167, v171, v219
	v_fma_f32 v172, v167, v172, v220
	v_fma_f32 v219, -v170, v174, v213
	v_fma_f32 v220, v170, v173, v214
	v_fma_f32 v173, v169, v173, v219
	v_fma_f32 v174, v169, v174, v220
	v_mul_f32_e32 v183, v118, v38
	v_mul_f32_e32 v187, v118, v70
	v_fma_f32 v183, -v134, v70, v183
	v_fmac_f32_e32 v187, v134, v38
	v_mul_f32_e32 v184, v119, v39
	v_mul_f32_e32 v188, v119, v71
	v_fma_f32 v184, -v135, v71, v184
	v_fmac_f32_e32 v188, v135, v39
	v_mul_f32_e32 v185, v120, v40
	v_mul_f32_e32 v189, v120, v72
	v_fma_f32 v185, -v136, v72, v185
	v_fmac_f32_e32 v189, v136, v40
	v_mul_f32_e32 v186, v121, v41
	v_mul_f32_e32 v190, v121, v73
	v_fma_f32 v186, -v137, v73, v186
	v_fmac_f32_e32 v190, v137, v41
	v_fmac_f32_e32 v183, v122, v42
	v_fmac_f32_e32 v187, v122, v74
	v_fma_f32 v183, -v138, v74, v183
	v_fmac_f32_e32 v187, v138, v42
	v_fmac_f32_e32 v184, v123, v43
	v_fmac_f32_e32 v188, v123, v75
	v_fma_f32 v184, -v139, v75, v184
	v_fmac_f32_e32 v188, v139, v43
	v_fmac_f32_e32 v185, v124, v44
	v_fmac_f32_e32 v189, v124, v76
	v_fma_f32 v185, -v140, v76, v185
	v_fmac_f32_e32 v189, v140, v44
	v_fmac_f32_e32 v186, v125, v45
	v_fmac_f32_e32 v190, v125, v77
	v_fma_f32 v186, -v141, v77, v186
	v_fmac_f32_e32 v190, v141, v45
	v_fmac_f32_e32 v183, v126, v46
	v_fmac_f32_e32 v187, v126, v78
	v_fma_f32 v183, -v142, v78, v183
	v_fmac_f32_e32 v187, v142, v46
	v_fmac_f32_e32 v184, v127, v47
	v_fmac_f32_e32 v188, v127, v79
	v_fma_f32 v184, -v143, v79, v184
	v_fmac_f32_e32 v188, v143, v47
	v_fmac_f32_e32 v185, v128, v48
	v_fmac_f32_e32 v189, v128, v80
	v_fma_f32 v185, -v144, v80, v185
	v_fmac_f32_e32 v189, v144, v48
	v_fmac_f32_e32 v186, v129, v49
	v_fmac_f32_e32 v190, v129, v81
	v_fma_f32 v186, -v145, v81, v186
	v_fmac_f32_e32 v190, v145, v49
	v_fmac_f32_e32 v183, v130, v50
	v_fmac_f32_e32 v187, v130, v82
	v_fma_f32 v183, -v146, v82, v183
	v_fmac_f32_e32 v187, v146, v50
	v_fmac_f32_e32 v184, v131, v51
	v_fmac_f32_e32 v188, v131, v83
	v_fma_f32 v184, -v147, v83, v184
	v_fmac_f32_e32 v188, v147, v51
	v_fmac_f32_e32 v185, v132, v52
	v_fmac_f32_e32 v189, v132, v84
	v_fma_f32 v185, -v148, v84, v185
	v_fmac_f32_e32 v189, v148, v52
	v_fmac_f32_e32 v186, v133, v53
	v_fmac_f32_e32 v190, v133, v85
	v_fma_f32 v186, -v149, v85, v186
	v_fmac_f32_e32 v190, v149, v53
	s_waitcnt vmcnt(7)
	v_mfma_f32_32x32x16_bf16 v[22:37], v[192:195], v[6:9], 0
	v_mfma_f32_32x32x16_bf16 v[54:69], v[192:195], v[14:17], 0
	v_mfma_f32_32x32x16_bf16 v[38:53], v[192:195], v[10:13], 0
	v_mfma_f32_32x32x16_bf16 v[70:85], v[192:195], v[18:21], 0
	s_add_u32 s42, s32, 0x180000
	s_addc_u32 s43, s33, 0
	global_load_dwordx4 v[192:195], v210, s[42:43]
	v_add_f32_e32 v219, v175, v176
	v_add_f32_e32 v220, v177, v178
	v_add_f32_e32 v211, v219, v220
	v_add_f32_e32 v219, v179, v180
	v_add_f32_e32 v220, v181, v182
	v_add_f32_e32 v212, v219, v220
	v_add_f32_e32 v219, v183, v184
	v_add_f32_e32 v220, v185, v186
	v_add_f32_e32 v213, v219, v220
	v_add_f32_e32 v219, v187, v188
	v_add_f32_e32 v220, v189, v190
	v_add_f32_e32 v214, v219, v220
	ds_bpermute_b32 v215, v208, v211
	ds_bpermute_b32 v216, v208, v212
	ds_bpermute_b32 v217, v208, v213
	ds_bpermute_b32 v218, v208, v214
	v_mul_f32_e32 v175, v86, v22
	v_mul_f32_e32 v179, v86, v54
	v_fma_f32 v175, -v102, v54, v175
	v_fmac_f32_e32 v179, v102, v22
	v_mul_f32_e32 v176, v87, v23
	v_mul_f32_e32 v180, v87, v55
	v_fma_f32 v176, -v103, v55, v176
	v_fmac_f32_e32 v180, v103, v23
	v_mul_f32_e32 v177, v88, v24
	v_mul_f32_e32 v181, v88, v56
	v_fma_f32 v177, -v104, v56, v177
	v_fmac_f32_e32 v181, v104, v24
	v_mul_f32_e32 v178, v89, v25
	v_mul_f32_e32 v182, v89, v57
	v_fma_f32 v178, -v105, v57, v178
	v_fmac_f32_e32 v182, v105, v25
	v_fmac_f32_e32 v175, v90, v26
	v_fmac_f32_e32 v179, v90, v58
	v_fma_f32 v175, -v106, v58, v175
	v_fmac_f32_e32 v179, v106, v26
	v_fmac_f32_e32 v176, v91, v27
	v_fmac_f32_e32 v180, v91, v59
	v_fma_f32 v176, -v107, v59, v176
	v_fmac_f32_e32 v180, v107, v27
	v_fmac_f32_e32 v177, v92, v28
	v_fmac_f32_e32 v181, v92, v60
	v_fma_f32 v177, -v108, v60, v177
	v_fmac_f32_e32 v181, v108, v28
	v_fmac_f32_e32 v178, v93, v29
	v_fmac_f32_e32 v182, v93, v61
	v_fma_f32 v178, -v109, v61, v178
	v_fmac_f32_e32 v182, v109, v29
	v_fmac_f32_e32 v175, v94, v30
	v_fmac_f32_e32 v179, v94, v62
	v_fma_f32 v175, -v110, v62, v175
	v_fmac_f32_e32 v179, v110, v30
	v_fmac_f32_e32 v176, v95, v31
	v_fmac_f32_e32 v180, v95, v63
	v_fma_f32 v176, -v111, v63, v176
	v_fmac_f32_e32 v180, v111, v31
	v_fmac_f32_e32 v177, v96, v32
	v_fmac_f32_e32 v181, v96, v64
	v_fma_f32 v177, -v112, v64, v177
	v_fmac_f32_e32 v181, v112, v32
	v_fmac_f32_e32 v178, v97, v33
	v_fmac_f32_e32 v182, v97, v65
	v_fma_f32 v178, -v113, v65, v178
	v_fmac_f32_e32 v182, v113, v33
	v_fmac_f32_e32 v175, v98, v34
	v_fmac_f32_e32 v179, v98, v66
	v_fma_f32 v175, -v114, v66, v175
	v_fmac_f32_e32 v179, v114, v34
	v_fmac_f32_e32 v176, v99, v35
	v_fmac_f32_e32 v180, v99, v67
	v_fma_f32 v176, -v115, v67, v176
	v_fmac_f32_e32 v180, v115, v35
	v_fmac_f32_e32 v177, v100, v36
	v_fmac_f32_e32 v181, v100, v68
	v_fma_f32 v177, -v116, v68, v177
	v_fmac_f32_e32 v181, v116, v36
	v_fmac_f32_e32 v178, v101, v37
	v_fmac_f32_e32 v182, v101, v69
	v_fma_f32 v178, -v117, v69, v178
	v_fmac_f32_e32 v182, v117, v37
	s_waitcnt lgkmcnt(0)
	v_add_f32_e32 v211, v211, v215
	v_add_f32_e32 v212, v212, v216
	v_add_f32_e32 v213, v213, v217
	v_add_f32_e32 v214, v214, v218
	v_fma_f32 v219, -v168, v172, v211
	v_fma_f32 v220, v168, v171, v212
	v_fma_f32 v171, v167, v171, v219
	v_fma_f32 v172, v167, v172, v220
	v_fma_f32 v219, -v170, v174, v213
	v_fma_f32 v220, v170, v173, v214
	v_fma_f32 v173, v169, v173, v219
	v_fma_f32 v174, v169, v174, v220
	s_add_u32 s42, s38, 0x200
	s_addc_u32 s43, s39, 0
	s_mov_b64 exec, s[12:13]
	global_store_dword v209, v171, s[42:43]
	global_store_dword v209, v172, s[42:43] offset:256
	global_store_dword v209, v173, s[42:43] offset:128
	global_store_dword v209, v174, s[42:43] offset:384
	s_mov_b64 exec, -1
	v_mul_f32_e32 v183, v118, v38
	v_mul_f32_e32 v187, v118, v70
	v_fma_f32 v183, -v134, v70, v183
	v_fmac_f32_e32 v187, v134, v38
	v_mul_f32_e32 v184, v119, v39
	v_mul_f32_e32 v188, v119, v71
	v_fma_f32 v184, -v135, v71, v184
	v_fmac_f32_e32 v188, v135, v39
	v_mul_f32_e32 v185, v120, v40
	v_mul_f32_e32 v189, v120, v72
	v_fma_f32 v185, -v136, v72, v185
	v_fmac_f32_e32 v189, v136, v40
	v_mul_f32_e32 v186, v121, v41
	v_mul_f32_e32 v190, v121, v73
	v_fma_f32 v186, -v137, v73, v186
	v_fmac_f32_e32 v190, v137, v41
	v_fmac_f32_e32 v183, v122, v42
	v_fmac_f32_e32 v187, v122, v74
	v_fma_f32 v183, -v138, v74, v183
	v_fmac_f32_e32 v187, v138, v42
	v_fmac_f32_e32 v184, v123, v43
	v_fmac_f32_e32 v188, v123, v75
	v_fma_f32 v184, -v139, v75, v184
	v_fmac_f32_e32 v188, v139, v43
	v_fmac_f32_e32 v185, v124, v44
	v_fmac_f32_e32 v189, v124, v76
	v_fma_f32 v185, -v140, v76, v185
	v_fmac_f32_e32 v189, v140, v44
	v_fmac_f32_e32 v186, v125, v45
	v_fmac_f32_e32 v190, v125, v77
	v_fma_f32 v186, -v141, v77, v186
	v_fmac_f32_e32 v190, v141, v45
	v_fmac_f32_e32 v183, v126, v46
	v_fmac_f32_e32 v187, v126, v78
	v_fma_f32 v183, -v142, v78, v183
	v_fmac_f32_e32 v187, v142, v46
	v_fmac_f32_e32 v184, v127, v47
	v_fmac_f32_e32 v188, v127, v79
	v_fma_f32 v184, -v143, v79, v184
	v_fmac_f32_e32 v188, v143, v47
	v_fmac_f32_e32 v185, v128, v48
	v_fmac_f32_e32 v189, v128, v80
	v_fma_f32 v185, -v144, v80, v185
	v_fmac_f32_e32 v189, v144, v48
	v_fmac_f32_e32 v186, v129, v49
	v_fmac_f32_e32 v190, v129, v81
	v_fma_f32 v186, -v145, v81, v186
	v_fmac_f32_e32 v190, v145, v49
	v_fmac_f32_e32 v183, v130, v50
	v_fmac_f32_e32 v187, v130, v82
	v_fma_f32 v183, -v146, v82, v183
	v_fmac_f32_e32 v187, v146, v50
	v_fmac_f32_e32 v184, v131, v51
	v_fmac_f32_e32 v188, v131, v83
	v_fma_f32 v184, -v147, v83, v184
	v_fmac_f32_e32 v188, v147, v51
	v_fmac_f32_e32 v185, v132, v52
	v_fmac_f32_e32 v189, v132, v84
	v_fma_f32 v185, -v148, v84, v185
	v_fmac_f32_e32 v189, v148, v52
	v_fmac_f32_e32 v186, v133, v53
	v_fmac_f32_e32 v190, v133, v85
	v_fma_f32 v186, -v149, v85, v186
	v_fmac_f32_e32 v190, v149, v53
	s_waitcnt vmcnt(7)
	v_mfma_f32_32x32x16_bf16 v[22:37], v[196:199], v[6:9], 0
	v_mfma_f32_32x32x16_bf16 v[54:69], v[196:199], v[14:17], 0
	v_mfma_f32_32x32x16_bf16 v[38:53], v[196:199], v[10:13], 0
	v_mfma_f32_32x32x16_bf16 v[70:85], v[196:199], v[18:21], 0
	s_add_u32 s42, s32, 0x1a0000
	s_addc_u32 s43, s33, 0
	global_load_dwordx4 v[196:199], v210, s[42:43]
	v_add_f32_e32 v219, v175, v176
	v_add_f32_e32 v220, v177, v178
	v_add_f32_e32 v211, v219, v220
	v_add_f32_e32 v219, v179, v180
	v_add_f32_e32 v220, v181, v182
	v_add_f32_e32 v212, v219, v220
	v_add_f32_e32 v219, v183, v184
	v_add_f32_e32 v220, v185, v186
	v_add_f32_e32 v213, v219, v220
	v_add_f32_e32 v219, v187, v188
	v_add_f32_e32 v220, v189, v190
	v_add_f32_e32 v214, v219, v220
	ds_bpermute_b32 v215, v208, v211
	ds_bpermute_b32 v216, v208, v212
	ds_bpermute_b32 v217, v208, v213
	ds_bpermute_b32 v218, v208, v214
	v_mul_f32_e32 v175, v86, v22
	v_mul_f32_e32 v179, v86, v54
	v_fma_f32 v175, -v102, v54, v175
	v_fmac_f32_e32 v179, v102, v22
	v_mul_f32_e32 v176, v87, v23
	v_mul_f32_e32 v180, v87, v55
	v_fma_f32 v176, -v103, v55, v176
	v_fmac_f32_e32 v180, v103, v23
	v_mul_f32_e32 v177, v88, v24
	v_mul_f32_e32 v181, v88, v56
	v_fma_f32 v177, -v104, v56, v177
	v_fmac_f32_e32 v181, v104, v24
	v_mul_f32_e32 v178, v89, v25
	v_mul_f32_e32 v182, v89, v57
	v_fma_f32 v178, -v105, v57, v178
	v_fmac_f32_e32 v182, v105, v25
	v_fmac_f32_e32 v175, v90, v26
	v_fmac_f32_e32 v179, v90, v58
	v_fma_f32 v175, -v106, v58, v175
	v_fmac_f32_e32 v179, v106, v26
	v_fmac_f32_e32 v176, v91, v27
	v_fmac_f32_e32 v180, v91, v59
	v_fma_f32 v176, -v107, v59, v176
	v_fmac_f32_e32 v180, v107, v27
	v_fmac_f32_e32 v177, v92, v28
	v_fmac_f32_e32 v181, v92, v60
	v_fma_f32 v177, -v108, v60, v177
	v_fmac_f32_e32 v181, v108, v28
	v_fmac_f32_e32 v178, v93, v29
	v_fmac_f32_e32 v182, v93, v61
	v_fma_f32 v178, -v109, v61, v178
	v_fmac_f32_e32 v182, v109, v29
	v_fmac_f32_e32 v175, v94, v30
	v_fmac_f32_e32 v179, v94, v62
	v_fma_f32 v175, -v110, v62, v175
	v_fmac_f32_e32 v179, v110, v30
	v_fmac_f32_e32 v176, v95, v31
	v_fmac_f32_e32 v180, v95, v63
	v_fma_f32 v176, -v111, v63, v176
	v_fmac_f32_e32 v180, v111, v31
	v_fmac_f32_e32 v177, v96, v32
	v_fmac_f32_e32 v181, v96, v64
	v_fma_f32 v177, -v112, v64, v177
	v_fmac_f32_e32 v181, v112, v32
	v_fmac_f32_e32 v178, v97, v33
	v_fmac_f32_e32 v182, v97, v65
	v_fma_f32 v178, -v113, v65, v178
	v_fmac_f32_e32 v182, v113, v33
	v_fmac_f32_e32 v175, v98, v34
	v_fmac_f32_e32 v179, v98, v66
	v_fma_f32 v175, -v114, v66, v175
	v_fmac_f32_e32 v179, v114, v34
	v_fmac_f32_e32 v176, v99, v35
	v_fmac_f32_e32 v180, v99, v67
	v_fma_f32 v176, -v115, v67, v176
	v_fmac_f32_e32 v180, v115, v35
	v_fmac_f32_e32 v177, v100, v36
	v_fmac_f32_e32 v181, v100, v68
	v_fma_f32 v177, -v116, v68, v177
	v_fmac_f32_e32 v181, v116, v36
	v_fmac_f32_e32 v178, v101, v37
	v_fmac_f32_e32 v182, v101, v69
	v_fma_f32 v178, -v117, v69, v178
	v_fmac_f32_e32 v182, v117, v37
	s_waitcnt lgkmcnt(0)
	v_add_f32_e32 v211, v211, v215
	v_add_f32_e32 v212, v212, v216
	v_add_f32_e32 v213, v213, v217
	v_add_f32_e32 v214, v214, v218
	v_fma_f32 v219, -v168, v172, v211
	v_fma_f32 v220, v168, v171, v212
	v_fma_f32 v171, v167, v171, v219
	v_fma_f32 v172, v167, v172, v220
	v_fma_f32 v219, -v170, v174, v213
	v_fma_f32 v220, v170, v173, v214
	v_fma_f32 v173, v169, v173, v219
	v_fma_f32 v174, v169, v174, v220
	v_mul_f32_e32 v183, v118, v38
	v_mul_f32_e32 v187, v118, v70
	v_fma_f32 v183, -v134, v70, v183
	v_fmac_f32_e32 v187, v134, v38
	v_mul_f32_e32 v184, v119, v39
	v_mul_f32_e32 v188, v119, v71
	v_fma_f32 v184, -v135, v71, v184
	v_fmac_f32_e32 v188, v135, v39
	v_mul_f32_e32 v185, v120, v40
	v_mul_f32_e32 v189, v120, v72
	v_fma_f32 v185, -v136, v72, v185
	v_fmac_f32_e32 v189, v136, v40
	v_mul_f32_e32 v186, v121, v41
	v_mul_f32_e32 v190, v121, v73
	v_fma_f32 v186, -v137, v73, v186
	v_fmac_f32_e32 v190, v137, v41
	v_fmac_f32_e32 v183, v122, v42
	v_fmac_f32_e32 v187, v122, v74
	v_fma_f32 v183, -v138, v74, v183
	v_fmac_f32_e32 v187, v138, v42
	v_fmac_f32_e32 v184, v123, v43
	v_fmac_f32_e32 v188, v123, v75
	v_fma_f32 v184, -v139, v75, v184
	v_fmac_f32_e32 v188, v139, v43
	v_fmac_f32_e32 v185, v124, v44
	v_fmac_f32_e32 v189, v124, v76
	v_fma_f32 v185, -v140, v76, v185
	v_fmac_f32_e32 v189, v140, v44
	v_fmac_f32_e32 v186, v125, v45
	v_fmac_f32_e32 v190, v125, v77
	v_fma_f32 v186, -v141, v77, v186
	v_fmac_f32_e32 v190, v141, v45
	v_fmac_f32_e32 v183, v126, v46
	v_fmac_f32_e32 v187, v126, v78
	v_fma_f32 v183, -v142, v78, v183
	v_fmac_f32_e32 v187, v142, v46
	v_fmac_f32_e32 v184, v127, v47
	v_fmac_f32_e32 v188, v127, v79
	v_fma_f32 v184, -v143, v79, v184
	v_fmac_f32_e32 v188, v143, v47
	v_fmac_f32_e32 v185, v128, v48
	v_fmac_f32_e32 v189, v128, v80
	v_fma_f32 v185, -v144, v80, v185
	v_fmac_f32_e32 v189, v144, v48
	v_fmac_f32_e32 v186, v129, v49
	v_fmac_f32_e32 v190, v129, v81
	v_fma_f32 v186, -v145, v81, v186
	v_fmac_f32_e32 v190, v145, v49
	v_fmac_f32_e32 v183, v130, v50
	v_fmac_f32_e32 v187, v130, v82
	v_fma_f32 v183, -v146, v82, v183
	v_fmac_f32_e32 v187, v146, v50
	v_fmac_f32_e32 v184, v131, v51
	v_fmac_f32_e32 v188, v131, v83
	v_fma_f32 v184, -v147, v83, v184
	v_fmac_f32_e32 v188, v147, v51
	v_fmac_f32_e32 v185, v132, v52
	v_fmac_f32_e32 v189, v132, v84
	v_fma_f32 v185, -v148, v84, v185
	v_fmac_f32_e32 v189, v148, v52
	v_fmac_f32_e32 v186, v133, v53
	v_fmac_f32_e32 v190, v133, v85
	v_fma_f32 v186, -v149, v85, v186
	v_fmac_f32_e32 v190, v149, v53
	s_waitcnt vmcnt(7)
	v_mfma_f32_32x32x16_bf16 v[22:37], v[200:203], v[6:9], 0
	v_mfma_f32_32x32x16_bf16 v[54:69], v[200:203], v[14:17], 0
	v_mfma_f32_32x32x16_bf16 v[38:53], v[200:203], v[10:13], 0
	v_mfma_f32_32x32x16_bf16 v[70:85], v[200:203], v[18:21], 0
	s_add_u32 s42, s32, 0x1c0000
	s_addc_u32 s43, s33, 0
	global_load_dwordx4 v[200:203], v210, s[42:43]
	v_add_f32_e32 v219, v175, v176
	v_add_f32_e32 v220, v177, v178
	v_add_f32_e32 v211, v219, v220
	v_add_f32_e32 v219, v179, v180
	v_add_f32_e32 v220, v181, v182
	v_add_f32_e32 v212, v219, v220
	v_add_f32_e32 v219, v183, v184
	v_add_f32_e32 v220, v185, v186
	v_add_f32_e32 v213, v219, v220
	v_add_f32_e32 v219, v187, v188
	v_add_f32_e32 v220, v189, v190
	v_add_f32_e32 v214, v219, v220
	ds_bpermute_b32 v215, v208, v211
	ds_bpermute_b32 v216, v208, v212
	ds_bpermute_b32 v217, v208, v213
	ds_bpermute_b32 v218, v208, v214
	v_mul_f32_e32 v175, v86, v22
	v_mul_f32_e32 v179, v86, v54
	v_fma_f32 v175, -v102, v54, v175
	v_fmac_f32_e32 v179, v102, v22
	v_mul_f32_e32 v176, v87, v23
	v_mul_f32_e32 v180, v87, v55
	v_fma_f32 v176, -v103, v55, v176
	v_fmac_f32_e32 v180, v103, v23
	v_mul_f32_e32 v177, v88, v24
	v_mul_f32_e32 v181, v88, v56
	v_fma_f32 v177, -v104, v56, v177
	v_fmac_f32_e32 v181, v104, v24
	v_mul_f32_e32 v178, v89, v25
	v_mul_f32_e32 v182, v89, v57
	v_fma_f32 v178, -v105, v57, v178
	v_fmac_f32_e32 v182, v105, v25
	v_fmac_f32_e32 v175, v90, v26
	v_fmac_f32_e32 v179, v90, v58
	v_fma_f32 v175, -v106, v58, v175
	v_fmac_f32_e32 v179, v106, v26
	v_fmac_f32_e32 v176, v91, v27
	v_fmac_f32_e32 v180, v91, v59
	v_fma_f32 v176, -v107, v59, v176
	v_fmac_f32_e32 v180, v107, v27
	v_fmac_f32_e32 v177, v92, v28
	v_fmac_f32_e32 v181, v92, v60
	v_fma_f32 v177, -v108, v60, v177
	v_fmac_f32_e32 v181, v108, v28
	v_fmac_f32_e32 v178, v93, v29
	v_fmac_f32_e32 v182, v93, v61
	v_fma_f32 v178, -v109, v61, v178
	v_fmac_f32_e32 v182, v109, v29
	v_fmac_f32_e32 v175, v94, v30
	v_fmac_f32_e32 v179, v94, v62
	v_fma_f32 v175, -v110, v62, v175
	v_fmac_f32_e32 v179, v110, v30
	v_fmac_f32_e32 v176, v95, v31
	v_fmac_f32_e32 v180, v95, v63
	v_fma_f32 v176, -v111, v63, v176
	v_fmac_f32_e32 v180, v111, v31
	v_fmac_f32_e32 v177, v96, v32
	v_fmac_f32_e32 v181, v96, v64
	v_fma_f32 v177, -v112, v64, v177
	v_fmac_f32_e32 v181, v112, v32
	v_fmac_f32_e32 v178, v97, v33
	v_fmac_f32_e32 v182, v97, v65
	v_fma_f32 v178, -v113, v65, v178
	v_fmac_f32_e32 v182, v113, v33
	v_fmac_f32_e32 v175, v98, v34
	v_fmac_f32_e32 v179, v98, v66
	v_fma_f32 v175, -v114, v66, v175
	v_fmac_f32_e32 v179, v114, v34
	v_fmac_f32_e32 v176, v99, v35
	v_fmac_f32_e32 v180, v99, v67
	v_fma_f32 v176, -v115, v67, v176
	v_fmac_f32_e32 v180, v115, v35
	v_fmac_f32_e32 v177, v100, v36
	v_fmac_f32_e32 v181, v100, v68
	v_fma_f32 v177, -v116, v68, v177
	v_fmac_f32_e32 v181, v116, v36
	v_fmac_f32_e32 v178, v101, v37
	v_fmac_f32_e32 v182, v101, v69
	v_fma_f32 v178, -v117, v69, v178
	v_fmac_f32_e32 v182, v117, v37
	s_waitcnt lgkmcnt(0)
	v_add_f32_e32 v211, v211, v215
	v_add_f32_e32 v212, v212, v216
	v_add_f32_e32 v213, v213, v217
	v_add_f32_e32 v214, v214, v218
	v_fma_f32 v219, -v168, v172, v211
	v_fma_f32 v220, v168, v171, v212
	v_fma_f32 v171, v167, v171, v219
	v_fma_f32 v172, v167, v172, v220
	v_fma_f32 v219, -v170, v174, v213
	v_fma_f32 v220, v170, v173, v214
	v_fma_f32 v173, v169, v173, v219
	v_fma_f32 v174, v169, v174, v220
	v_mul_f32_e32 v183, v118, v38
	v_mul_f32_e32 v187, v118, v70
	v_fma_f32 v183, -v134, v70, v183
	v_fmac_f32_e32 v187, v134, v38
	v_mul_f32_e32 v184, v119, v39
	v_mul_f32_e32 v188, v119, v71
	v_fma_f32 v184, -v135, v71, v184
	v_fmac_f32_e32 v188, v135, v39
	v_mul_f32_e32 v185, v120, v40
	v_mul_f32_e32 v189, v120, v72
	v_fma_f32 v185, -v136, v72, v185
	v_fmac_f32_e32 v189, v136, v40
	v_mul_f32_e32 v186, v121, v41
	v_mul_f32_e32 v190, v121, v73
	v_fma_f32 v186, -v137, v73, v186
	v_fmac_f32_e32 v190, v137, v41
	v_fmac_f32_e32 v183, v122, v42
	v_fmac_f32_e32 v187, v122, v74
	v_fma_f32 v183, -v138, v74, v183
	v_fmac_f32_e32 v187, v138, v42
	v_fmac_f32_e32 v184, v123, v43
	v_fmac_f32_e32 v188, v123, v75
	v_fma_f32 v184, -v139, v75, v184
	v_fmac_f32_e32 v188, v139, v43
	v_fmac_f32_e32 v185, v124, v44
	v_fmac_f32_e32 v189, v124, v76
	v_fma_f32 v185, -v140, v76, v185
	v_fmac_f32_e32 v189, v140, v44
	v_fmac_f32_e32 v186, v125, v45
	v_fmac_f32_e32 v190, v125, v77
	v_fma_f32 v186, -v141, v77, v186
	v_fmac_f32_e32 v190, v141, v45
	v_fmac_f32_e32 v183, v126, v46
	v_fmac_f32_e32 v187, v126, v78
	v_fma_f32 v183, -v142, v78, v183
	v_fmac_f32_e32 v187, v142, v46
	v_fmac_f32_e32 v184, v127, v47
	v_fmac_f32_e32 v188, v127, v79
	v_fma_f32 v184, -v143, v79, v184
	v_fmac_f32_e32 v188, v143, v47
	v_fmac_f32_e32 v185, v128, v48
	v_fmac_f32_e32 v189, v128, v80
	v_fma_f32 v185, -v144, v80, v185
	v_fmac_f32_e32 v189, v144, v48
	v_fmac_f32_e32 v186, v129, v49
	v_fmac_f32_e32 v190, v129, v81
	v_fma_f32 v186, -v145, v81, v186
	v_fmac_f32_e32 v190, v145, v49
	v_fmac_f32_e32 v183, v130, v50
	v_fmac_f32_e32 v187, v130, v82
	v_fma_f32 v183, -v146, v82, v183
	v_fmac_f32_e32 v187, v146, v50
	v_fmac_f32_e32 v184, v131, v51
	v_fmac_f32_e32 v188, v131, v83
	v_fma_f32 v184, -v147, v83, v184
	v_fmac_f32_e32 v188, v147, v51
	v_fmac_f32_e32 v185, v132, v52
	v_fmac_f32_e32 v189, v132, v84
	v_fma_f32 v185, -v148, v84, v185
	v_fmac_f32_e32 v189, v148, v52
	v_fmac_f32_e32 v186, v133, v53
	v_fmac_f32_e32 v190, v133, v85
	v_fma_f32 v186, -v149, v85, v186
	v_fmac_f32_e32 v190, v149, v53
	s_waitcnt vmcnt(7)
	v_mfma_f32_32x32x16_bf16 v[22:37], v[204:207], v[6:9], 0
	v_mfma_f32_32x32x16_bf16 v[54:69], v[204:207], v[14:17], 0
	v_mfma_f32_32x32x16_bf16 v[38:53], v[204:207], v[10:13], 0
	v_mfma_f32_32x32x16_bf16 v[70:85], v[204:207], v[18:21], 0
	s_add_u32 s42, s32, 0x1e0000
	s_addc_u32 s43, s33, 0
	global_load_dwordx4 v[204:207], v210, s[42:43]
	v_add_f32_e32 v219, v175, v176
	v_add_f32_e32 v220, v177, v178
	v_add_f32_e32 v211, v219, v220
	v_add_f32_e32 v219, v179, v180
	v_add_f32_e32 v220, v181, v182
	v_add_f32_e32 v212, v219, v220
	v_add_f32_e32 v219, v183, v184
	v_add_f32_e32 v220, v185, v186
	v_add_f32_e32 v213, v219, v220
	v_add_f32_e32 v219, v187, v188
	v_add_f32_e32 v220, v189, v190
	v_add_f32_e32 v214, v219, v220
	ds_bpermute_b32 v215, v208, v211
	ds_bpermute_b32 v216, v208, v212
	ds_bpermute_b32 v217, v208, v213
	ds_bpermute_b32 v218, v208, v214
	v_mul_f32_e32 v175, v86, v22
	v_mul_f32_e32 v179, v86, v54
	v_fma_f32 v175, -v102, v54, v175
	v_fmac_f32_e32 v179, v102, v22
	v_mul_f32_e32 v176, v87, v23
	v_mul_f32_e32 v180, v87, v55
	v_fma_f32 v176, -v103, v55, v176
	v_fmac_f32_e32 v180, v103, v23
	v_mul_f32_e32 v177, v88, v24
	v_mul_f32_e32 v181, v88, v56
	v_fma_f32 v177, -v104, v56, v177
	v_fmac_f32_e32 v181, v104, v24
	v_mul_f32_e32 v178, v89, v25
	v_mul_f32_e32 v182, v89, v57
	v_fma_f32 v178, -v105, v57, v178
	v_fmac_f32_e32 v182, v105, v25
	v_fmac_f32_e32 v175, v90, v26
	v_fmac_f32_e32 v179, v90, v58
	v_fma_f32 v175, -v106, v58, v175
	v_fmac_f32_e32 v179, v106, v26
	v_fmac_f32_e32 v176, v91, v27
	v_fmac_f32_e32 v180, v91, v59
	v_fma_f32 v176, -v107, v59, v176
	v_fmac_f32_e32 v180, v107, v27
	v_fmac_f32_e32 v177, v92, v28
	v_fmac_f32_e32 v181, v92, v60
	v_fma_f32 v177, -v108, v60, v177
	v_fmac_f32_e32 v181, v108, v28
	v_fmac_f32_e32 v178, v93, v29
	v_fmac_f32_e32 v182, v93, v61
	v_fma_f32 v178, -v109, v61, v178
	v_fmac_f32_e32 v182, v109, v29
	v_fmac_f32_e32 v175, v94, v30
	v_fmac_f32_e32 v179, v94, v62
	v_fma_f32 v175, -v110, v62, v175
	v_fmac_f32_e32 v179, v110, v30
	v_fmac_f32_e32 v176, v95, v31
	v_fmac_f32_e32 v180, v95, v63
	v_fma_f32 v176, -v111, v63, v176
	v_fmac_f32_e32 v180, v111, v31
	v_fmac_f32_e32 v177, v96, v32
	v_fmac_f32_e32 v181, v96, v64
	v_fma_f32 v177, -v112, v64, v177
	v_fmac_f32_e32 v181, v112, v32
	v_fmac_f32_e32 v178, v97, v33
	v_fmac_f32_e32 v182, v97, v65
	v_fma_f32 v178, -v113, v65, v178
	v_fmac_f32_e32 v182, v113, v33
	v_fmac_f32_e32 v175, v98, v34
	v_fmac_f32_e32 v179, v98, v66
	v_fma_f32 v175, -v114, v66, v175
	v_fmac_f32_e32 v179, v114, v34
	v_fmac_f32_e32 v176, v99, v35
	v_fmac_f32_e32 v180, v99, v67
	v_fma_f32 v176, -v115, v67, v176
	v_fmac_f32_e32 v180, v115, v35
	v_fmac_f32_e32 v177, v100, v36
	v_fmac_f32_e32 v181, v100, v68
	v_fma_f32 v177, -v116, v68, v177
	v_fmac_f32_e32 v181, v116, v36
	v_fmac_f32_e32 v178, v101, v37
	v_fmac_f32_e32 v182, v101, v69
	v_fma_f32 v178, -v117, v69, v178
	v_fmac_f32_e32 v182, v117, v37
	s_waitcnt lgkmcnt(0)
	v_add_f32_e32 v211, v211, v215
	v_add_f32_e32 v212, v212, v216
	v_add_f32_e32 v213, v213, v217
	v_add_f32_e32 v214, v214, v218
	v_fma_f32 v219, -v168, v172, v211
	v_fma_f32 v220, v168, v171, v212
	v_fma_f32 v171, v167, v171, v219
	v_fma_f32 v172, v167, v172, v220
	v_fma_f32 v219, -v170, v174, v213
	v_fma_f32 v220, v170, v173, v214
	v_fma_f32 v173, v169, v173, v219
	v_fma_f32 v174, v169, v174, v220
	v_mul_f32_e32 v183, v118, v38
	v_mul_f32_e32 v187, v118, v70
	v_fma_f32 v183, -v134, v70, v183
	v_fmac_f32_e32 v187, v134, v38
	v_mul_f32_e32 v184, v119, v39
	v_mul_f32_e32 v188, v119, v71
	v_fma_f32 v184, -v135, v71, v184
	v_fmac_f32_e32 v188, v135, v39
	v_mul_f32_e32 v185, v120, v40
	v_mul_f32_e32 v189, v120, v72
	v_fma_f32 v185, -v136, v72, v185
	v_fmac_f32_e32 v189, v136, v40
	v_mul_f32_e32 v186, v121, v41
	v_mul_f32_e32 v190, v121, v73
	v_fma_f32 v186, -v137, v73, v186
	v_fmac_f32_e32 v190, v137, v41
	v_fmac_f32_e32 v183, v122, v42
	v_fmac_f32_e32 v187, v122, v74
	v_fma_f32 v183, -v138, v74, v183
	v_fmac_f32_e32 v187, v138, v42
	v_fmac_f32_e32 v184, v123, v43
	v_fmac_f32_e32 v188, v123, v75
	v_fma_f32 v184, -v139, v75, v184
	v_fmac_f32_e32 v188, v139, v43
	v_fmac_f32_e32 v185, v124, v44
	v_fmac_f32_e32 v189, v124, v76
	v_fma_f32 v185, -v140, v76, v185
	v_fmac_f32_e32 v189, v140, v44
	v_fmac_f32_e32 v186, v125, v45
	v_fmac_f32_e32 v190, v125, v77
	v_fma_f32 v186, -v141, v77, v186
	v_fmac_f32_e32 v190, v141, v45
	v_fmac_f32_e32 v183, v126, v46
	v_fmac_f32_e32 v187, v126, v78
	v_fma_f32 v183, -v142, v78, v183
	v_fmac_f32_e32 v187, v142, v46
	v_fmac_f32_e32 v184, v127, v47
	v_fmac_f32_e32 v188, v127, v79
	v_fma_f32 v184, -v143, v79, v184
	v_fmac_f32_e32 v188, v143, v47
	v_fmac_f32_e32 v185, v128, v48
	v_fmac_f32_e32 v189, v128, v80
	v_fma_f32 v185, -v144, v80, v185
	v_fmac_f32_e32 v189, v144, v48
	v_fmac_f32_e32 v186, v129, v49
	v_fmac_f32_e32 v190, v129, v81
	v_fma_f32 v186, -v145, v81, v186
	v_fmac_f32_e32 v190, v145, v49
	v_fmac_f32_e32 v183, v130, v50
	v_fmac_f32_e32 v187, v130, v82
	v_fma_f32 v183, -v146, v82, v183
	v_fmac_f32_e32 v187, v146, v50
	v_fmac_f32_e32 v184, v131, v51
	v_fmac_f32_e32 v188, v131, v83
	v_fma_f32 v184, -v147, v83, v184
	v_fmac_f32_e32 v188, v147, v51
	v_fmac_f32_e32 v185, v132, v52
	v_fmac_f32_e32 v189, v132, v84
	v_fma_f32 v185, -v148, v84, v185
	v_fmac_f32_e32 v189, v148, v52
	v_fmac_f32_e32 v186, v133, v53
	v_fmac_f32_e32 v190, v133, v85
	v_fma_f32 v186, -v149, v85, v186
	v_fmac_f32_e32 v190, v149, v53
	s_waitcnt vmcnt(7)
	v_mfma_f32_32x32x16_bf16 v[22:37], v[192:195], v[6:9], 0
	v_mfma_f32_32x32x16_bf16 v[54:69], v[192:195], v[14:17], 0
	v_mfma_f32_32x32x16_bf16 v[38:53], v[192:195], v[10:13], 0
	v_mfma_f32_32x32x16_bf16 v[70:85], v[192:195], v[18:21], 0
	v_add_f32_e32 v219, v175, v176
	v_add_f32_e32 v220, v177, v178
	v_add_f32_e32 v211, v219, v220
	v_add_f32_e32 v219, v179, v180
	v_add_f32_e32 v220, v181, v182
	v_add_f32_e32 v212, v219, v220
	v_add_f32_e32 v219, v183, v184
	v_add_f32_e32 v220, v185, v186
	v_add_f32_e32 v213, v219, v220
	v_add_f32_e32 v219, v187, v188
	v_add_f32_e32 v220, v189, v190
	v_add_f32_e32 v214, v219, v220
	ds_bpermute_b32 v215, v208, v211
	ds_bpermute_b32 v216, v208, v212
	ds_bpermute_b32 v217, v208, v213
	ds_bpermute_b32 v218, v208, v214
	v_mul_f32_e32 v175, v86, v22
	v_mul_f32_e32 v179, v86, v54
	v_fma_f32 v175, -v102, v54, v175
	v_fmac_f32_e32 v179, v102, v22
	v_mul_f32_e32 v176, v87, v23
	v_mul_f32_e32 v180, v87, v55
	v_fma_f32 v176, -v103, v55, v176
	v_fmac_f32_e32 v180, v103, v23
	v_mul_f32_e32 v177, v88, v24
	v_mul_f32_e32 v181, v88, v56
	v_fma_f32 v177, -v104, v56, v177
	v_fmac_f32_e32 v181, v104, v24
	v_mul_f32_e32 v178, v89, v25
	v_mul_f32_e32 v182, v89, v57
	v_fma_f32 v178, -v105, v57, v178
	v_fmac_f32_e32 v182, v105, v25
	v_fmac_f32_e32 v175, v90, v26
	v_fmac_f32_e32 v179, v90, v58
	v_fma_f32 v175, -v106, v58, v175
	v_fmac_f32_e32 v179, v106, v26
	v_fmac_f32_e32 v176, v91, v27
	v_fmac_f32_e32 v180, v91, v59
	v_fma_f32 v176, -v107, v59, v176
	v_fmac_f32_e32 v180, v107, v27
	v_fmac_f32_e32 v177, v92, v28
	v_fmac_f32_e32 v181, v92, v60
	v_fma_f32 v177, -v108, v60, v177
	v_fmac_f32_e32 v181, v108, v28
	v_fmac_f32_e32 v178, v93, v29
	v_fmac_f32_e32 v182, v93, v61
	v_fma_f32 v178, -v109, v61, v178
	v_fmac_f32_e32 v182, v109, v29
	v_fmac_f32_e32 v175, v94, v30
	v_fmac_f32_e32 v179, v94, v62
	v_fma_f32 v175, -v110, v62, v175
	v_fmac_f32_e32 v179, v110, v30
	v_fmac_f32_e32 v176, v95, v31
	v_fmac_f32_e32 v180, v95, v63
	v_fma_f32 v176, -v111, v63, v176
	v_fmac_f32_e32 v180, v111, v31
	v_fmac_f32_e32 v177, v96, v32
	v_fmac_f32_e32 v181, v96, v64
	v_fma_f32 v177, -v112, v64, v177
	v_fmac_f32_e32 v181, v112, v32
	v_fmac_f32_e32 v178, v97, v33
	v_fmac_f32_e32 v182, v97, v65
	v_fma_f32 v178, -v113, v65, v178
	v_fmac_f32_e32 v182, v113, v33
	v_fmac_f32_e32 v175, v98, v34
	v_fmac_f32_e32 v179, v98, v66
	v_fma_f32 v175, -v114, v66, v175
	v_fmac_f32_e32 v179, v114, v34
	v_fmac_f32_e32 v176, v99, v35
	v_fmac_f32_e32 v180, v99, v67
	v_fma_f32 v176, -v115, v67, v176
	v_fmac_f32_e32 v180, v115, v35
	v_fmac_f32_e32 v177, v100, v36
	v_fmac_f32_e32 v181, v100, v68
	v_fma_f32 v177, -v116, v68, v177
	v_fmac_f32_e32 v181, v116, v36
	v_fmac_f32_e32 v178, v101, v37
	v_fmac_f32_e32 v182, v101, v69
	v_fma_f32 v178, -v117, v69, v178
	v_fmac_f32_e32 v182, v117, v37
	s_waitcnt lgkmcnt(0)
	v_add_f32_e32 v211, v211, v215
	v_add_f32_e32 v212, v212, v216
	v_add_f32_e32 v213, v213, v217
	v_add_f32_e32 v214, v214, v218
	v_fma_f32 v219, -v168, v172, v211
	v_fma_f32 v220, v168, v171, v212
	v_fma_f32 v171, v167, v171, v219
	v_fma_f32 v172, v167, v172, v220
	v_fma_f32 v219, -v170, v174, v213
	v_fma_f32 v220, v170, v173, v214
	v_fma_f32 v173, v169, v173, v219
	v_fma_f32 v174, v169, v174, v220
	s_add_u32 s42, s38, 0x400
	s_addc_u32 s43, s39, 0
	s_mov_b64 exec, s[12:13]
	global_store_dword v209, v171, s[42:43]
	global_store_dword v209, v172, s[42:43] offset:256
	global_store_dword v209, v173, s[42:43] offset:128
	global_store_dword v209, v174, s[42:43] offset:384
	s_mov_b64 exec, -1
	v_mul_f32_e32 v183, v118, v38
	v_mul_f32_e32 v187, v118, v70
	v_fma_f32 v183, -v134, v70, v183
	v_fmac_f32_e32 v187, v134, v38
	v_mul_f32_e32 v184, v119, v39
	v_mul_f32_e32 v188, v119, v71
	v_fma_f32 v184, -v135, v71, v184
	v_fmac_f32_e32 v188, v135, v39
	v_mul_f32_e32 v185, v120, v40
	v_mul_f32_e32 v189, v120, v72
	v_fma_f32 v185, -v136, v72, v185
	v_fmac_f32_e32 v189, v136, v40
	v_mul_f32_e32 v186, v121, v41
	v_mul_f32_e32 v190, v121, v73
	v_fma_f32 v186, -v137, v73, v186
	v_fmac_f32_e32 v190, v137, v41
	v_fmac_f32_e32 v183, v122, v42
	v_fmac_f32_e32 v187, v122, v74
	v_fma_f32 v183, -v138, v74, v183
	v_fmac_f32_e32 v187, v138, v42
	v_fmac_f32_e32 v184, v123, v43
	v_fmac_f32_e32 v188, v123, v75
	v_fma_f32 v184, -v139, v75, v184
	v_fmac_f32_e32 v188, v139, v43
	v_fmac_f32_e32 v185, v124, v44
	v_fmac_f32_e32 v189, v124, v76
	v_fma_f32 v185, -v140, v76, v185
	v_fmac_f32_e32 v189, v140, v44
	v_fmac_f32_e32 v186, v125, v45
	v_fmac_f32_e32 v190, v125, v77
	v_fma_f32 v186, -v141, v77, v186
	v_fmac_f32_e32 v190, v141, v45
	v_fmac_f32_e32 v183, v126, v46
	v_fmac_f32_e32 v187, v126, v78
	v_fma_f32 v183, -v142, v78, v183
	v_fmac_f32_e32 v187, v142, v46
	v_fmac_f32_e32 v184, v127, v47
	v_fmac_f32_e32 v188, v127, v79
	v_fma_f32 v184, -v143, v79, v184
	v_fmac_f32_e32 v188, v143, v47
	v_fmac_f32_e32 v185, v128, v48
	v_fmac_f32_e32 v189, v128, v80
	v_fma_f32 v185, -v144, v80, v185
	v_fmac_f32_e32 v189, v144, v48
	v_fmac_f32_e32 v186, v129, v49
	v_fmac_f32_e32 v190, v129, v81
	v_fma_f32 v186, -v145, v81, v186
	v_fmac_f32_e32 v190, v145, v49
	v_fmac_f32_e32 v183, v130, v50
	v_fmac_f32_e32 v187, v130, v82
	v_fma_f32 v183, -v146, v82, v183
	v_fmac_f32_e32 v187, v146, v50
	v_fmac_f32_e32 v184, v131, v51
	v_fmac_f32_e32 v188, v131, v83
	v_fma_f32 v184, -v147, v83, v184
	v_fmac_f32_e32 v188, v147, v51
	v_fmac_f32_e32 v185, v132, v52
	v_fmac_f32_e32 v189, v132, v84
	v_fma_f32 v185, -v148, v84, v185
	v_fmac_f32_e32 v189, v148, v52
	v_fmac_f32_e32 v186, v133, v53
	v_fmac_f32_e32 v190, v133, v85
	v_fma_f32 v186, -v149, v85, v186
	v_fmac_f32_e32 v190, v149, v53
	s_waitcnt vmcnt(6)
	v_mfma_f32_32x32x16_bf16 v[22:37], v[196:199], v[6:9], 0
	v_mfma_f32_32x32x16_bf16 v[54:69], v[196:199], v[14:17], 0
	v_mfma_f32_32x32x16_bf16 v[38:53], v[196:199], v[10:13], 0
	v_mfma_f32_32x32x16_bf16 v[70:85], v[196:199], v[18:21], 0
	v_add_f32_e32 v219, v175, v176
	v_add_f32_e32 v220, v177, v178
	v_add_f32_e32 v211, v219, v220
	v_add_f32_e32 v219, v179, v180
	v_add_f32_e32 v220, v181, v182
	v_add_f32_e32 v212, v219, v220
	v_add_f32_e32 v219, v183, v184
	v_add_f32_e32 v220, v185, v186
	v_add_f32_e32 v213, v219, v220
	v_add_f32_e32 v219, v187, v188
	v_add_f32_e32 v220, v189, v190
	v_add_f32_e32 v214, v219, v220
	ds_bpermute_b32 v215, v208, v211
	ds_bpermute_b32 v216, v208, v212
	ds_bpermute_b32 v217, v208, v213
	ds_bpermute_b32 v218, v208, v214
	v_mul_f32_e32 v175, v86, v22
	v_mul_f32_e32 v179, v86, v54
	v_fma_f32 v175, -v102, v54, v175
	v_fmac_f32_e32 v179, v102, v22
	v_mul_f32_e32 v176, v87, v23
	v_mul_f32_e32 v180, v87, v55
	v_fma_f32 v176, -v103, v55, v176
	v_fmac_f32_e32 v180, v103, v23
	v_mul_f32_e32 v177, v88, v24
	v_mul_f32_e32 v181, v88, v56
	v_fma_f32 v177, -v104, v56, v177
	v_fmac_f32_e32 v181, v104, v24
	v_mul_f32_e32 v178, v89, v25
	v_mul_f32_e32 v182, v89, v57
	v_fma_f32 v178, -v105, v57, v178
	v_fmac_f32_e32 v182, v105, v25
	v_fmac_f32_e32 v175, v90, v26
	v_fmac_f32_e32 v179, v90, v58
	v_fma_f32 v175, -v106, v58, v175
	v_fmac_f32_e32 v179, v106, v26
	v_fmac_f32_e32 v176, v91, v27
	v_fmac_f32_e32 v180, v91, v59
	v_fma_f32 v176, -v107, v59, v176
	v_fmac_f32_e32 v180, v107, v27
	v_fmac_f32_e32 v177, v92, v28
	v_fmac_f32_e32 v181, v92, v60
	v_fma_f32 v177, -v108, v60, v177
	v_fmac_f32_e32 v181, v108, v28
	v_fmac_f32_e32 v178, v93, v29
	v_fmac_f32_e32 v182, v93, v61
	v_fma_f32 v178, -v109, v61, v178
	v_fmac_f32_e32 v182, v109, v29
	v_fmac_f32_e32 v175, v94, v30
	v_fmac_f32_e32 v179, v94, v62
	v_fma_f32 v175, -v110, v62, v175
	v_fmac_f32_e32 v179, v110, v30
	v_fmac_f32_e32 v176, v95, v31
	v_fmac_f32_e32 v180, v95, v63
	v_fma_f32 v176, -v111, v63, v176
	v_fmac_f32_e32 v180, v111, v31
	v_fmac_f32_e32 v177, v96, v32
	v_fmac_f32_e32 v181, v96, v64
	v_fma_f32 v177, -v112, v64, v177
	v_fmac_f32_e32 v181, v112, v32
	v_fmac_f32_e32 v178, v97, v33
	v_fmac_f32_e32 v182, v97, v65
	v_fma_f32 v178, -v113, v65, v178
	v_fmac_f32_e32 v182, v113, v33
	v_fmac_f32_e32 v175, v98, v34
	v_fmac_f32_e32 v179, v98, v66
	v_fma_f32 v175, -v114, v66, v175
	v_fmac_f32_e32 v179, v114, v34
	v_fmac_f32_e32 v176, v99, v35
	v_fmac_f32_e32 v180, v99, v67
	v_fma_f32 v176, -v115, v67, v176
	v_fmac_f32_e32 v180, v115, v35
	v_fmac_f32_e32 v177, v100, v36
	v_fmac_f32_e32 v181, v100, v68
	v_fma_f32 v177, -v116, v68, v177
	v_fmac_f32_e32 v181, v116, v36
	v_fmac_f32_e32 v178, v101, v37
	v_fmac_f32_e32 v182, v101, v69
	v_fma_f32 v178, -v117, v69, v178
	v_fmac_f32_e32 v182, v117, v37
	s_waitcnt lgkmcnt(0)
	v_add_f32_e32 v211, v211, v215
	v_add_f32_e32 v212, v212, v216
	v_add_f32_e32 v213, v213, v217
	v_add_f32_e32 v214, v214, v218
	v_fma_f32 v219, -v168, v172, v211
	v_fma_f32 v220, v168, v171, v212
	v_fma_f32 v171, v167, v171, v219
	v_fma_f32 v172, v167, v172, v220
	v_fma_f32 v219, -v170, v174, v213
	v_fma_f32 v220, v170, v173, v214
	v_fma_f32 v173, v169, v173, v219
	v_fma_f32 v174, v169, v174, v220
	v_mul_f32_e32 v183, v118, v38
	v_mul_f32_e32 v187, v118, v70
	v_fma_f32 v183, -v134, v70, v183
	v_fmac_f32_e32 v187, v134, v38
	v_mul_f32_e32 v184, v119, v39
	v_mul_f32_e32 v188, v119, v71
	v_fma_f32 v184, -v135, v71, v184
	v_fmac_f32_e32 v188, v135, v39
	v_mul_f32_e32 v185, v120, v40
	v_mul_f32_e32 v189, v120, v72
	v_fma_f32 v185, -v136, v72, v185
	v_fmac_f32_e32 v189, v136, v40
	v_mul_f32_e32 v186, v121, v41
	v_mul_f32_e32 v190, v121, v73
	v_fma_f32 v186, -v137, v73, v186
	v_fmac_f32_e32 v190, v137, v41
	v_fmac_f32_e32 v183, v122, v42
	v_fmac_f32_e32 v187, v122, v74
	v_fma_f32 v183, -v138, v74, v183
	v_fmac_f32_e32 v187, v138, v42
	v_fmac_f32_e32 v184, v123, v43
	v_fmac_f32_e32 v188, v123, v75
	v_fma_f32 v184, -v139, v75, v184
	v_fmac_f32_e32 v188, v139, v43
	v_fmac_f32_e32 v185, v124, v44
	v_fmac_f32_e32 v189, v124, v76
	v_fma_f32 v185, -v140, v76, v185
	v_fmac_f32_e32 v189, v140, v44
	v_fmac_f32_e32 v186, v125, v45
	v_fmac_f32_e32 v190, v125, v77
	v_fma_f32 v186, -v141, v77, v186
	v_fmac_f32_e32 v190, v141, v45
	v_fmac_f32_e32 v183, v126, v46
	v_fmac_f32_e32 v187, v126, v78
	v_fma_f32 v183, -v142, v78, v183
	v_fmac_f32_e32 v187, v142, v46
	v_fmac_f32_e32 v184, v127, v47
	v_fmac_f32_e32 v188, v127, v79
	v_fma_f32 v184, -v143, v79, v184
	v_fmac_f32_e32 v188, v143, v47
	v_fmac_f32_e32 v185, v128, v48
	v_fmac_f32_e32 v189, v128, v80
	v_fma_f32 v185, -v144, v80, v185
	v_fmac_f32_e32 v189, v144, v48
	v_fmac_f32_e32 v186, v129, v49
	v_fmac_f32_e32 v190, v129, v81
	v_fma_f32 v186, -v145, v81, v186
	v_fmac_f32_e32 v190, v145, v49
	v_fmac_f32_e32 v183, v130, v50
	v_fmac_f32_e32 v187, v130, v82
	v_fma_f32 v183, -v146, v82, v183
	v_fmac_f32_e32 v187, v146, v50
	v_fmac_f32_e32 v184, v131, v51
	v_fmac_f32_e32 v188, v131, v83
	v_fma_f32 v184, -v147, v83, v184
	v_fmac_f32_e32 v188, v147, v51
	v_fmac_f32_e32 v185, v132, v52
	v_fmac_f32_e32 v189, v132, v84
	v_fma_f32 v185, -v148, v84, v185
	v_fmac_f32_e32 v189, v148, v52
	v_fmac_f32_e32 v186, v133, v53
	v_fmac_f32_e32 v190, v133, v85
	v_fma_f32 v186, -v149, v85, v186
	v_fmac_f32_e32 v190, v149, v53
	s_waitcnt vmcnt(5)
	v_mfma_f32_32x32x16_bf16 v[22:37], v[200:203], v[6:9], 0
	v_mfma_f32_32x32x16_bf16 v[54:69], v[200:203], v[14:17], 0
	v_mfma_f32_32x32x16_bf16 v[38:53], v[200:203], v[10:13], 0
	v_mfma_f32_32x32x16_bf16 v[70:85], v[200:203], v[18:21], 0
	v_add_f32_e32 v219, v175, v176
	v_add_f32_e32 v220, v177, v178
	v_add_f32_e32 v211, v219, v220
	v_add_f32_e32 v219, v179, v180
	v_add_f32_e32 v220, v181, v182
	v_add_f32_e32 v212, v219, v220
	v_add_f32_e32 v219, v183, v184
	v_add_f32_e32 v220, v185, v186
	v_add_f32_e32 v213, v219, v220
	v_add_f32_e32 v219, v187, v188
	v_add_f32_e32 v220, v189, v190
	v_add_f32_e32 v214, v219, v220
	ds_bpermute_b32 v215, v208, v211
	ds_bpermute_b32 v216, v208, v212
	ds_bpermute_b32 v217, v208, v213
	ds_bpermute_b32 v218, v208, v214
	v_mul_f32_e32 v175, v86, v22
	v_mul_f32_e32 v179, v86, v54
	v_fma_f32 v175, -v102, v54, v175
	v_fmac_f32_e32 v179, v102, v22
	v_mul_f32_e32 v176, v87, v23
	v_mul_f32_e32 v180, v87, v55
	v_fma_f32 v176, -v103, v55, v176
	v_fmac_f32_e32 v180, v103, v23
	v_mul_f32_e32 v177, v88, v24
	v_mul_f32_e32 v181, v88, v56
	v_fma_f32 v177, -v104, v56, v177
	v_fmac_f32_e32 v181, v104, v24
	v_mul_f32_e32 v178, v89, v25
	v_mul_f32_e32 v182, v89, v57
	v_fma_f32 v178, -v105, v57, v178
	v_fmac_f32_e32 v182, v105, v25
	v_fmac_f32_e32 v175, v90, v26
	v_fmac_f32_e32 v179, v90, v58
	v_fma_f32 v175, -v106, v58, v175
	v_fmac_f32_e32 v179, v106, v26
	v_fmac_f32_e32 v176, v91, v27
	v_fmac_f32_e32 v180, v91, v59
	v_fma_f32 v176, -v107, v59, v176
	v_fmac_f32_e32 v180, v107, v27
	v_fmac_f32_e32 v177, v92, v28
	v_fmac_f32_e32 v181, v92, v60
	v_fma_f32 v177, -v108, v60, v177
	v_fmac_f32_e32 v181, v108, v28
	v_fmac_f32_e32 v178, v93, v29
	v_fmac_f32_e32 v182, v93, v61
	v_fma_f32 v178, -v109, v61, v178
	v_fmac_f32_e32 v182, v109, v29
	v_fmac_f32_e32 v175, v94, v30
	v_fmac_f32_e32 v179, v94, v62
	v_fma_f32 v175, -v110, v62, v175
	v_fmac_f32_e32 v179, v110, v30
	v_fmac_f32_e32 v176, v95, v31
	v_fmac_f32_e32 v180, v95, v63
	v_fma_f32 v176, -v111, v63, v176
	v_fmac_f32_e32 v180, v111, v31
	v_fmac_f32_e32 v177, v96, v32
	v_fmac_f32_e32 v181, v96, v64
	v_fma_f32 v177, -v112, v64, v177
	v_fmac_f32_e32 v181, v112, v32
	v_fmac_f32_e32 v178, v97, v33
	v_fmac_f32_e32 v182, v97, v65
	v_fma_f32 v178, -v113, v65, v178
	v_fmac_f32_e32 v182, v113, v33
	v_fmac_f32_e32 v175, v98, v34
	v_fmac_f32_e32 v179, v98, v66
	v_fma_f32 v175, -v114, v66, v175
	v_fmac_f32_e32 v179, v114, v34
	v_fmac_f32_e32 v176, v99, v35
	v_fmac_f32_e32 v180, v99, v67
	v_fma_f32 v176, -v115, v67, v176
	v_fmac_f32_e32 v180, v115, v35
	v_fmac_f32_e32 v177, v100, v36
	v_fmac_f32_e32 v181, v100, v68
	v_fma_f32 v177, -v116, v68, v177
	v_fmac_f32_e32 v181, v116, v36
	v_fmac_f32_e32 v178, v101, v37
	v_fmac_f32_e32 v182, v101, v69
	v_fma_f32 v178, -v117, v69, v178
	v_fmac_f32_e32 v182, v117, v37
	s_waitcnt lgkmcnt(0)
	v_add_f32_e32 v211, v211, v215
	v_add_f32_e32 v212, v212, v216
	v_add_f32_e32 v213, v213, v217
	v_add_f32_e32 v214, v214, v218
	v_fma_f32 v219, -v168, v172, v211
	v_fma_f32 v220, v168, v171, v212
	v_fma_f32 v171, v167, v171, v219
	v_fma_f32 v172, v167, v172, v220
	v_fma_f32 v219, -v170, v174, v213
	v_fma_f32 v220, v170, v173, v214
	v_fma_f32 v173, v169, v173, v219
	v_fma_f32 v174, v169, v174, v220
	v_mul_f32_e32 v183, v118, v38
	v_mul_f32_e32 v187, v118, v70
	v_fma_f32 v183, -v134, v70, v183
	v_fmac_f32_e32 v187, v134, v38
	v_mul_f32_e32 v184, v119, v39
	v_mul_f32_e32 v188, v119, v71
	v_fma_f32 v184, -v135, v71, v184
	v_fmac_f32_e32 v188, v135, v39
	v_mul_f32_e32 v185, v120, v40
	v_mul_f32_e32 v189, v120, v72
	v_fma_f32 v185, -v136, v72, v185
	v_fmac_f32_e32 v189, v136, v40
	v_mul_f32_e32 v186, v121, v41
	v_mul_f32_e32 v190, v121, v73
	v_fma_f32 v186, -v137, v73, v186
	v_fmac_f32_e32 v190, v137, v41
	v_fmac_f32_e32 v183, v122, v42
	v_fmac_f32_e32 v187, v122, v74
	v_fma_f32 v183, -v138, v74, v183
	v_fmac_f32_e32 v187, v138, v42
	v_fmac_f32_e32 v184, v123, v43
	v_fmac_f32_e32 v188, v123, v75
	v_fma_f32 v184, -v139, v75, v184
	v_fmac_f32_e32 v188, v139, v43
	v_fmac_f32_e32 v185, v124, v44
	v_fmac_f32_e32 v189, v124, v76
	v_fma_f32 v185, -v140, v76, v185
	v_fmac_f32_e32 v189, v140, v44
	v_fmac_f32_e32 v186, v125, v45
	v_fmac_f32_e32 v190, v125, v77
	v_fma_f32 v186, -v141, v77, v186
	v_fmac_f32_e32 v190, v141, v45
	v_fmac_f32_e32 v183, v126, v46
	v_fmac_f32_e32 v187, v126, v78
	v_fma_f32 v183, -v142, v78, v183
	v_fmac_f32_e32 v187, v142, v46
	v_fmac_f32_e32 v184, v127, v47
	v_fmac_f32_e32 v188, v127, v79
	v_fma_f32 v184, -v143, v79, v184
	v_fmac_f32_e32 v188, v143, v47
	v_fmac_f32_e32 v185, v128, v48
	v_fmac_f32_e32 v189, v128, v80
	v_fma_f32 v185, -v144, v80, v185
	v_fmac_f32_e32 v189, v144, v48
	v_fmac_f32_e32 v186, v129, v49
	v_fmac_f32_e32 v190, v129, v81
	v_fma_f32 v186, -v145, v81, v186
	v_fmac_f32_e32 v190, v145, v49
	v_fmac_f32_e32 v183, v130, v50
	v_fmac_f32_e32 v187, v130, v82
	v_fma_f32 v183, -v146, v82, v183
	v_fmac_f32_e32 v187, v146, v50
	v_fmac_f32_e32 v184, v131, v51
	v_fmac_f32_e32 v188, v131, v83
	v_fma_f32 v184, -v147, v83, v184
	v_fmac_f32_e32 v188, v147, v51
	v_fmac_f32_e32 v185, v132, v52
	v_fmac_f32_e32 v189, v132, v84
	v_fma_f32 v185, -v148, v84, v185
	v_fmac_f32_e32 v189, v148, v52
	v_fmac_f32_e32 v186, v133, v53
	v_fmac_f32_e32 v190, v133, v85
	v_fma_f32 v186, -v149, v85, v186
	v_fmac_f32_e32 v190, v149, v53
	s_waitcnt vmcnt(4)
	v_mfma_f32_32x32x16_bf16 v[22:37], v[204:207], v[6:9], 0
	v_mfma_f32_32x32x16_bf16 v[54:69], v[204:207], v[14:17], 0
	v_mfma_f32_32x32x16_bf16 v[38:53], v[204:207], v[10:13], 0
	v_mfma_f32_32x32x16_bf16 v[70:85], v[204:207], v[18:21], 0
	v_add_f32_e32 v219, v175, v176
	v_add_f32_e32 v220, v177, v178
	v_add_f32_e32 v211, v219, v220
	v_add_f32_e32 v219, v179, v180
	v_add_f32_e32 v220, v181, v182
	v_add_f32_e32 v212, v219, v220
	v_add_f32_e32 v219, v183, v184
	v_add_f32_e32 v220, v185, v186
	v_add_f32_e32 v213, v219, v220
	v_add_f32_e32 v219, v187, v188
	v_add_f32_e32 v220, v189, v190
	v_add_f32_e32 v214, v219, v220
	ds_bpermute_b32 v215, v208, v211
	ds_bpermute_b32 v216, v208, v212
	ds_bpermute_b32 v217, v208, v213
	ds_bpermute_b32 v218, v208, v214
	v_mul_f32_e32 v175, v86, v22
	v_mul_f32_e32 v179, v86, v54
	v_fma_f32 v175, -v102, v54, v175
	v_fmac_f32_e32 v179, v102, v22
	v_mul_f32_e32 v176, v87, v23
	v_mul_f32_e32 v180, v87, v55
	v_fma_f32 v176, -v103, v55, v176
	v_fmac_f32_e32 v180, v103, v23
	v_mul_f32_e32 v177, v88, v24
	v_mul_f32_e32 v181, v88, v56
	v_fma_f32 v177, -v104, v56, v177
	v_fmac_f32_e32 v181, v104, v24
	v_mul_f32_e32 v178, v89, v25
	v_mul_f32_e32 v182, v89, v57
	v_fma_f32 v178, -v105, v57, v178
	v_fmac_f32_e32 v182, v105, v25
	v_fmac_f32_e32 v175, v90, v26
	v_fmac_f32_e32 v179, v90, v58
	v_fma_f32 v175, -v106, v58, v175
	v_fmac_f32_e32 v179, v106, v26
	v_fmac_f32_e32 v176, v91, v27
	v_fmac_f32_e32 v180, v91, v59
	v_fma_f32 v176, -v107, v59, v176
	v_fmac_f32_e32 v180, v107, v27
	v_fmac_f32_e32 v177, v92, v28
	v_fmac_f32_e32 v181, v92, v60
	v_fma_f32 v177, -v108, v60, v177
	v_fmac_f32_e32 v181, v108, v28
	v_fmac_f32_e32 v178, v93, v29
	v_fmac_f32_e32 v182, v93, v61
	v_fma_f32 v178, -v109, v61, v178
	v_fmac_f32_e32 v182, v109, v29
	v_fmac_f32_e32 v175, v94, v30
	v_fmac_f32_e32 v179, v94, v62
	v_fma_f32 v175, -v110, v62, v175
	v_fmac_f32_e32 v179, v110, v30
	v_fmac_f32_e32 v176, v95, v31
	v_fmac_f32_e32 v180, v95, v63
	v_fma_f32 v176, -v111, v63, v176
	v_fmac_f32_e32 v180, v111, v31
	v_fmac_f32_e32 v177, v96, v32
	v_fmac_f32_e32 v181, v96, v64
	v_fma_f32 v177, -v112, v64, v177
	v_fmac_f32_e32 v181, v112, v32
	v_fmac_f32_e32 v178, v97, v33
	v_fmac_f32_e32 v182, v97, v65
	v_fma_f32 v178, -v113, v65, v178
	v_fmac_f32_e32 v182, v113, v33
	v_fmac_f32_e32 v175, v98, v34
	v_fmac_f32_e32 v179, v98, v66
	v_fma_f32 v175, -v114, v66, v175
	v_fmac_f32_e32 v179, v114, v34
	v_fmac_f32_e32 v176, v99, v35
	v_fmac_f32_e32 v180, v99, v67
	v_fma_f32 v176, -v115, v67, v176
	v_fmac_f32_e32 v180, v115, v35
	v_fmac_f32_e32 v177, v100, v36
	v_fmac_f32_e32 v181, v100, v68
	v_fma_f32 v177, -v116, v68, v177
	v_fmac_f32_e32 v181, v116, v36
	v_fmac_f32_e32 v178, v101, v37
	v_fmac_f32_e32 v182, v101, v69
	v_fma_f32 v178, -v117, v69, v178
	v_fmac_f32_e32 v182, v117, v37
	s_waitcnt lgkmcnt(0)
	v_add_f32_e32 v211, v211, v215
	v_add_f32_e32 v212, v212, v216
	v_add_f32_e32 v213, v213, v217
	v_add_f32_e32 v214, v214, v218
	v_fma_f32 v219, -v168, v172, v211
	v_fma_f32 v220, v168, v171, v212
	v_fma_f32 v171, v167, v171, v219
	v_fma_f32 v172, v167, v172, v220
	v_fma_f32 v219, -v170, v174, v213
	v_fma_f32 v220, v170, v173, v214
	v_fma_f32 v173, v169, v173, v219
	v_fma_f32 v174, v169, v174, v220
	v_mul_f32_e32 v183, v118, v38
	v_mul_f32_e32 v187, v118, v70
	v_fma_f32 v183, -v134, v70, v183
	v_fmac_f32_e32 v187, v134, v38
	v_mul_f32_e32 v184, v119, v39
	v_mul_f32_e32 v188, v119, v71
	v_fma_f32 v184, -v135, v71, v184
	v_fmac_f32_e32 v188, v135, v39
	v_mul_f32_e32 v185, v120, v40
	v_mul_f32_e32 v189, v120, v72
	v_fma_f32 v185, -v136, v72, v185
	v_fmac_f32_e32 v189, v136, v40
	v_mul_f32_e32 v186, v121, v41
	v_mul_f32_e32 v190, v121, v73
	v_fma_f32 v186, -v137, v73, v186
	v_fmac_f32_e32 v190, v137, v41
	v_fmac_f32_e32 v183, v122, v42
	v_fmac_f32_e32 v187, v122, v74
	v_fma_f32 v183, -v138, v74, v183
	v_fmac_f32_e32 v187, v138, v42
	v_fmac_f32_e32 v184, v123, v43
	v_fmac_f32_e32 v188, v123, v75
	v_fma_f32 v184, -v139, v75, v184
	v_fmac_f32_e32 v188, v139, v43
	v_fmac_f32_e32 v185, v124, v44
	v_fmac_f32_e32 v189, v124, v76
	v_fma_f32 v185, -v140, v76, v185
	v_fmac_f32_e32 v189, v140, v44
	v_fmac_f32_e32 v186, v125, v45
	v_fmac_f32_e32 v190, v125, v77
	v_fma_f32 v186, -v141, v77, v186
	v_fmac_f32_e32 v190, v141, v45
	v_fmac_f32_e32 v183, v126, v46
	v_fmac_f32_e32 v187, v126, v78
	v_fma_f32 v183, -v142, v78, v183
	v_fmac_f32_e32 v187, v142, v46
	v_fmac_f32_e32 v184, v127, v47
	v_fmac_f32_e32 v188, v127, v79
	v_fma_f32 v184, -v143, v79, v184
	v_fmac_f32_e32 v188, v143, v47
	v_fmac_f32_e32 v185, v128, v48
	v_fmac_f32_e32 v189, v128, v80
	v_fma_f32 v185, -v144, v80, v185
	v_fmac_f32_e32 v189, v144, v48
	v_fmac_f32_e32 v186, v129, v49
	v_fmac_f32_e32 v190, v129, v81
	v_fma_f32 v186, -v145, v81, v186
	v_fmac_f32_e32 v190, v145, v49
	v_fmac_f32_e32 v183, v130, v50
	v_fmac_f32_e32 v187, v130, v82
	v_fma_f32 v183, -v146, v82, v183
	v_fmac_f32_e32 v187, v146, v50
	v_fmac_f32_e32 v184, v131, v51
	v_fmac_f32_e32 v188, v131, v83
	v_fma_f32 v184, -v147, v83, v184
	v_fmac_f32_e32 v188, v147, v51
	v_fmac_f32_e32 v185, v132, v52
	v_fmac_f32_e32 v189, v132, v84
	v_fma_f32 v185, -v148, v84, v185
	v_fmac_f32_e32 v189, v148, v52
	v_fmac_f32_e32 v186, v133, v53
	v_fmac_f32_e32 v190, v133, v85
	v_fma_f32 v186, -v149, v85, v186
	v_fmac_f32_e32 v190, v149, v53
	v_add_f32_e32 v219, v175, v176
	v_add_f32_e32 v220, v177, v178
	v_add_f32_e32 v211, v219, v220
	v_add_f32_e32 v219, v179, v180
	v_add_f32_e32 v220, v181, v182
	v_add_f32_e32 v212, v219, v220
	v_add_f32_e32 v219, v183, v184
	v_add_f32_e32 v220, v185, v186
	v_add_f32_e32 v213, v219, v220
	v_add_f32_e32 v219, v187, v188
	v_add_f32_e32 v220, v189, v190
	v_add_f32_e32 v214, v219, v220
	ds_bpermute_b32 v215, v208, v211
	ds_bpermute_b32 v216, v208, v212
	ds_bpermute_b32 v217, v208, v213
	ds_bpermute_b32 v218, v208, v214
	s_waitcnt lgkmcnt(0)
	v_add_f32_e32 v211, v211, v215
	v_add_f32_e32 v212, v212, v216
	v_add_f32_e32 v213, v213, v217
	v_add_f32_e32 v214, v214, v218
	v_fma_f32 v219, -v168, v172, v211
	v_fma_f32 v220, v168, v171, v212
	v_fma_f32 v171, v167, v171, v219
	v_fma_f32 v172, v167, v172, v220
	v_fma_f32 v219, -v170, v174, v213
	v_fma_f32 v220, v170, v173, v214
	v_fma_f32 v173, v169, v173, v219
	v_fma_f32 v174, v169, v174, v220
	s_add_u32 s42, s38, 0x600
	s_addc_u32 s43, s39, 0
	s_mov_b64 exec, s[12:13]
	global_store_dword v209, v171, s[42:43]
	global_store_dword v209, v172, s[42:43] offset:256
	global_store_dword v209, v173, s[42:43] offset:128
	global_store_dword v209, v174, s[42:43] offset:384
	s_mov_b64 exec, -1
	s_branch .LBB0_1334

.LBB0_1334:
	s_cmp_eq_u32 s98, 3
	s_cbranch_scc1 .Lpc_back
	s_waitcnt vmcnt(0)
	s_barrier
	s_mov_b64 s[0:1], exec
	v_readlane_b32 s2, v255, 11
	v_readlane_b32 s3, v255, 12
	s_and_b64 s[2:3], s[0:1], s[2:3]
	s_mov_b64 exec, s[2:3]
	s_cbranch_execz .LBB0_1386
	s_add_i32 s2, 0, 0x20000
	v_mov_b32_e32 v2, s2
	s_waitcnt vmcnt(0) expcnt(0) lgkmcnt(0)
	ds_read_b32 v4, v2
	s_add_i32 s2, 0, 0x20004
	v_mov_b32_e32 v2, s2
	ds_read_b32 v2, v2
	s_waitcnt lgkmcnt(1)
	v_cmp_ne_u32_e32 vcc, 0, v4
	s_cbranch_vccnz .LBB0_1350
	v_readlane_b32 s2, v255, 5
	v_readlane_b32 s3, v255, 6
	s_load_dwordx2 s[8:9], s[2:3], 0x4
	v_readlane_b32 s38, v255, 0
	v_readlane_b32 s39, v255, 1
	s_add_u32 s2, s38, 0x5e0200
	s_addc_u32 s3, s39, 0
	s_add_u32 s6, s38, 0x5e0400
	s_addc_u32 s7, s39, 0
	s_waitcnt lgkmcnt(0)
	s_mul_i32 s33, s8, s97
	s_add_u32 s8, s38, 0x5e0500
	s_mul_i32 s33, s33, s9
	s_addc_u32 s9, s39, 0
	s_add_u32 s10, s38, 0x5e0600
	s_addc_u32 s11, s39, 0
	s_add_u32 s12, s38, 0x5e0700
	s_addc_u32 s13, s39, 0
	s_add_u32 s14, s38, 0x5e0800
	s_addc_u32 s15, s39, 0
	s_add_u32 s16, s38, 0x5e0900
	s_addc_u32 s17, s39, 0
	s_add_u32 s18, s38, 0x5e0a00
	s_addc_u32 s19, s39, 0
	s_add_u32 s20, s38, 0x5e0b00
	s_addc_u32 s21, s39, 0
	s_add_u32 s22, s38, 0x5e0c00
	s_addc_u32 s23, s39, 0
	s_add_u32 s24, s38, 0x5e0d00
	s_addc_u32 s25, s39, 0
	s_add_u32 s26, s38, 0x5e0e00
	s_addc_u32 s27, s39, 0
	s_add_u32 s28, s38, 0x5e0f00
	s_addc_u32 s29, s39, 0
	s_add_u32 s30, s38, 0x5e1000
	s_addc_u32 s31, s39, 0
	s_add_u32 s34, s38, 0x5e1100
	s_addc_u32 s35, s39, 0
	s_add_u32 s36, s38, 0x5e1200
	s_addc_u32 s37, s39, 0
	s_add_u32 s38, s38, 0x5e1300
	s_addc_u32 s39, s39, 0
	s_mov_b32 s46, 1
	v_mov_b32_e32 v18, 0
	s_branch .LBB0_1338

.LBB0_1386:
	s_or_b64 exec, exec, s[0:1]
	v_readlane_b32 s2, v255, 3
	v_readlane_b32 s3, v255, 4
	s_waitcnt lgkmcnt(0)
	v_mov_b32_e32 v2, v0
	v_readlane_b32 s0, v255, 7
	s_barrier
	s_cmpk_gt_i32 s0, 0x3ff
	v_readfirstlane_b32 s6, v2
	s_cbranch_scc1 .LBB0_1414
	s_cmp_eq_u32 s97, 0x100
	s_cbranch_scc0 .Lpc_compiled
	v_readlane_b32 s6, v255, 7
	v_readlane_b32 s7, v255, 2
	s_nop 0
	s_lshr_b32 s7, s7, 6
	s_cmp_lt_u32 s7, 4
	s_cbranch_scc0 .Lpc_start
	s_lshl_b32 s92, s6, 2
	s_add_i32 s92, s92, s7
	s_mov_b32 s98, 3
	v_readlane_b32 s0, v255, 3
	v_readlane_b32 s1, v255, 4
	s_nop 4
	s_load_dwordx4 s[52:55], s[0:1], 0xc8
	s_load_dwordx2 s[2:3], s[0:1], 0xa0
	s_load_dwordx4 s[56:59], s[0:1], 0x28
	s_load_dwordx4 s[60:63], s[0:1], 0x90
	s_waitcnt lgkmcnt(0)
	s_add_u32 s64, s54, 0x5200000
	s_addc_u32 s65, s55, 0
	s_add_u32 s66, s54, 0x30000
	s_addc_u32 s67, s55, 0
	s_branch .LBB0_1315
.Lpc_back:
	s_mov_b32 s98, 0
.Lpc_start:
	s_mov_b64 exec, -1
	v_readlane_b32 s6, v255, 3
	v_readlane_b32 s7, v255, 4
	v_readlane_b32 s46, v255, 7
	v_readlane_b32 s47, v255, 2
	s_nop 4
	s_load_dwordx4 s[8:11], s[6:7], 0xc8
	s_load_dwordx2 s[12:13], s[6:7], 0xa0
	s_lshr_b32 s47, s47, 6
	s_mul_i32 s48, s47, 0x2400
	s_mov_b32 s42, -1
	s_mov_b32 s43, 0
	s_mov_b32 s44, 0xffff
	s_mov_b32 s45, 0xffff
	v_and_b32_e32 v209, 63, v0
	v_and_b32_e32 v210, 31, v209
	v_lshrrev_b32_e32 v211, 5, v209
	v_cmp_lt_u32_e64 s[40:41], 31, v209
	v_xor_b32_e32 v199, 32, v209
	v_lshlrev_b32_e32 v199, 2, v199
	v_mul_u32_u24_e32 v200, 0x48, v210
	v_lshl_add_u32 v200, v211, 3, v200
	v_add_u32_e32 v200, s48, v200
	v_and_b32_e32 v212, 15, v209
	v_lshrrev_b32_e32 v213, 2, v212
	v_and_b32_e32 v212, 3, v212
	v_bfe_u32 v214, v209, 4, 1
	v_lshl_add_u32 v213, v211, 3, v213
	v_mul_u32_u24_e32 v201, 0x48, v213
	v_lshl_add_u32 v212, v214, 2, v212
	v_lshl_add_u32 v201, v212, 3, v201
	v_add_u32_e32 v201, s48, v201
	v_lshlrev_b32_e32 v202, 2, v210
	v_lshl_add_u32 v202, v211, 8, v202
	v_add_u32_e32 v202, s48, v202
	v_lshrrev_b32_e32 v212, 1, v209
	v_and_b32_e32 v213, 1, v209
	v_lshlrev_b32_e32 v203, 6, v212
	v_lshl_add_u32 v203, v213, 5, v203
	v_add_u32_e32 v203, s48, v203
	v_lshlrev_b32_e32 v204, 12, v210
	v_lshl_add_u32 v204, v211, 4, v204
	v_lshlrev_b32_e32 v205, 12, v212
	v_lshl_add_u32 v205, v213, 4, v205
	v_lshlrev_b32_e32 v206, 2, v210
	v_lshlrev_b32_e32 v207, 3, v210
	v_lshlrev_b32_e32 v208, 4, v209
	v_lshlrev_b32_e32 v212, 3, v211
	v_sub_u32_e32 v212, v210, v212
	s_waitcnt lgkmcnt(0)
	v_mov_b32_e32 v254, v212
	v_cmp_gt_u32_e64 s[38:39], 16, v210

	.amdhsa_kernel _Z14fwd_megakernel6Params
		.amdhsa_group_segment_fixed_size 0
		.amdhsa_private_segment_fixed_size 0
		.amdhsa_kernarg_size 472
		.amdhsa_user_sgpr_count 2
		.amdhsa_user_sgpr_dispatch_ptr 0
		.amdhsa_user_sgpr_queue_ptr 0
		.amdhsa_user_sgpr_kernarg_segment_ptr 1
		.amdhsa_user_sgpr_dispatch_id 0
		.amdhsa_user_sgpr_kernarg_preload_length 0
		.amdhsa_user_sgpr_kernarg_preload_offset 0
		.amdhsa_user_sgpr_private_segment_size 0
		.amdhsa_uses_dynamic_stack 0
		.amdhsa_enable_private_segment 0
		.amdhsa_system_sgpr_workgroup_id_x 1
		.amdhsa_system_sgpr_workgroup_id_y 0
		.amdhsa_system_sgpr_workgroup_id_z 0
		.amdhsa_system_sgpr_workgroup_info 0
		.amdhsa_system_vgpr_workitem_id 0
		.amdhsa_next_free_vgpr 256
		.amdhsa_next_free_sgpr 102
		.amdhsa_accum_offset 256
		.amdhsa_reserve_vcc 1
		.amdhsa_float_round_mode_32 0
		.amdhsa_float_round_mode_16_64 0
		.amdhsa_float_denorm_mode_32 3
		.amdhsa_float_denorm_mode_16_64 3
		.amdhsa_dx10_clamp 1
		.amdhsa_ieee_mode 1
		.amdhsa_fp16_overflow 0
		.amdhsa_tg_split 0
		.amdhsa_exception_fp_ieee_invalid_op 0
		.amdhsa_exception_fp_denorm_src 0
		.amdhsa_exception_fp_ieee_div_zero 0
		.amdhsa_exception_fp_ieee_overflow 0
		.amdhsa_exception_fp_ieee_underflow 0
		.amdhsa_exception_fp_ieee_inexact 0
		.amdhsa_exception_int_div_zero 0
	.end_amdhsa_kernel

amdhsa.kernels:
  - .agpr_count:     0
    .args:
      - .offset:         0
        .size:           216
        .value_kind:     by_value
      - .offset:         216
        .size:           4
        .value_kind:     hidden_block_count_x
      - .offset:         220
        .size:           4
        .value_kind:     hidden_block_count_y
      - .offset:         224
        .size:           4
        .value_kind:     hidden_block_count_z
      - .offset:         228
        .size:           2
        .value_kind:     hidden_group_size_x
      - .offset:         230
        .size:           2
        .value_kind:     hidden_group_size_y
      - .offset:         232
        .size:           2
        .value_kind:     hidden_group_size_z
      - .offset:         234
        .size:           2
        .value_kind:     hidden_remainder_x
      - .offset:         236
        .size:           2
        .value_kind:     hidden_remainder_y
      - .offset:         238
        .size:           2
        .value_kind:     hidden_remainder_z
      - .offset:         256
        .size:           8
        .value_kind:     hidden_global_offset_x
      - .offset:         264
        .size:           8
        .value_kind:     hidden_global_offset_y
      - .offset:         272
        .size:           8
        .value_kind:     hidden_global_offset_z
      - .offset:         280
        .size:           2
        .value_kind:     hidden_grid_dims
      - .offset:         336
        .size:           4
        .value_kind:     hidden_dynamic_lds_size
    .group_segment_fixed_size: 0
    .kernarg_segment_align: 8
    .kernarg_segment_size: 472
    .language:       OpenCL C
    .language_version:
      - 2
      - 0
    .max_flat_workgroup_size: 512
    .name:           _Z14fwd_megakernel6Params
    .private_segment_fixed_size: 0
    .sgpr_count:     108
    .sgpr_spill_count: 68
    .symbol:         _Z14fwd_megakernel6Params.kd
    .uniform_work_group_size: 1
    .uses_dynamic_stack: false
    .vgpr_count:     256
    .vgpr_spill_count: 0
    .wavefront_size: 64
